# SwiGLU (and gate) epilogue bf16 activation stores: non-temporal hint, to keep the f32 residual stream cache-resident for the next residual epilogue
# speedup vs baseline: 1.0075x; 1.0075x over previous
.LBB0_165:
	v_ashrrev_i32_e32 v153, 31, v152
	v_lshlrev_b64 v[154:155], 6, v[152:153]
	v_lshl_add_u64 v[170:171], s[74:75], 0, v[154:155]
	s_waitcnt lgkmcnt(0)
	global_load_dwordx4 v[154:157], v[170:171], off
	global_load_dwordx4 v[162:165], v[170:171], off offset:16
	global_load_dwordx4 v[166:169], v[170:171], off offset:32
	s_nop 0
	global_load_dwordx4 v[170:173], v[170:171], off offset:48
	v_mov_b32_e32 v174, v124
	v_mov_b32_e32 v175, v116
	v_mov_b32_e32 v116, v125
	v_mov_b32_e32 v124, v126
	v_mov_b32_e32 v125, v118
	v_mov_b32_e32 v118, v127
	v_mov_b32_e32 v126, v120
	v_mov_b32_e32 v127, v112
	v_mov_b32_e32 v112, v121
	v_mov_b32_e32 v176, v122
	v_mov_b32_e32 v177, v114
	v_mov_b32_e32 v114, v123
	s_lshl_b32 s24, s24, 7
	v_mov_b64_e32 v[120:121], s[72:73]
	s_ashr_i32 s25, s24, 31
	v_mad_i64_i32 v[122:123], s[26:27], v152, s51, v[120:121]
	s_lshl_b64 s[24:25], s[24:25], 1
	v_lshl_add_u64 v[122:123], v[122:123], 0, s[24:25]
	v_lshl_add_u64 v[122:123], v[122:123], 0, s[6:7]
	s_waitcnt vmcnt(2)
	v_pk_add_f32 v[154:155], v[154:155], v[156:157]
	v_pk_add_f32 v[162:163], v[162:163], v[164:165]
	s_waitcnt vmcnt(0)
	v_pk_add_f32 v[166:167], v[166:167], v[168:169]
	v_pk_add_f32 v[170:171], v[170:171], v[172:173]
	v_pk_add_f32 v[154:155], v[154:155], v[162:163]
	v_pk_add_f32 v[166:167], v[166:167], v[170:171]
	v_mul_f32_e32 v116, v116, v117
	v_mul_f32_e32 v124, v124, v125
	v_mul_f32_e32 v118, v118, v119
	v_mul_f32_e32 v126, v126, v127
	v_pk_add_f32 v[154:155], v[154:155], v[166:167]
	v_mul_f32_e32 v174, v174, v175
	v_mul_f32_e32 v112, v112, v113
	v_mul_f32_e32 v176, v176, v177
	v_mul_f32_e32 v114, v114, v115
	v_add_f32_e32 v154, v154, v155
	v_fmamk_f32 v154, v154, 0x3a800000, v160
	v_rsq_f32_e32 v155, v154
	s_nop 0
	v_mul_f32_e32 v155, 0xbfb8aa3b, v155
	v_mul_f32_e32 v117, v155, v117
	v_mul_f32_e32 v125, v155, v125
	v_mul_f32_e32 v119, v155, v119
	v_mul_f32_e32 v127, v155, v127
	v_mul_f32_e32 v175, v155, v175
	v_mul_f32_e32 v113, v155, v113
	v_mul_f32_e32 v177, v155, v177
	v_mul_f32_e32 v115, v155, v115
	v_exp_f32_e32 v117, v117
	v_exp_f32_e32 v125, v125
	v_exp_f32_e32 v119, v119
	v_exp_f32_e32 v127, v127
	v_exp_f32_e32 v175, v175
	v_exp_f32_e32 v113, v113
	v_exp_f32_e32 v177, v177
	v_exp_f32_e32 v115, v115
	v_fma_f32 v117, v117, v154, v154
	v_fma_f32 v125, v125, v154, v154
	v_fma_f32 v119, v119, v154, v154
	v_fma_f32 v127, v127, v154, v154
	v_fma_f32 v175, v175, v154, v154
	v_fma_f32 v113, v113, v154, v154
	v_fma_f32 v177, v177, v154, v154
	v_fma_f32 v115, v115, v154, v154
	v_rcp_f32_e32 v117, v117
	v_rcp_f32_e32 v125, v125
	v_rcp_f32_e32 v119, v119
	v_rcp_f32_e32 v127, v127
	v_rcp_f32_e32 v175, v175
	v_rcp_f32_e32 v113, v113
	v_rcp_f32_e32 v177, v177
	v_rcp_f32_e32 v115, v115
	v_mul_f32_e32 v116, v116, v117
	v_mul_f32_e32 v124, v124, v125
	v_mul_f32_e32 v118, v118, v119
	v_mul_f32_e32 v126, v126, v127
	v_mul_f32_e32 v174, v174, v175
	v_mul_f32_e32 v112, v112, v113
	v_mul_f32_e32 v176, v176, v177
	v_mul_f32_e32 v114, v114, v115
	v_cvt_pk_bf16_f32 v113, v124, v118
	v_cvt_pk_bf16_f32 v115, v176, v114
	v_cvt_pk_bf16_f32 v114, v126, v112
	v_cvt_pk_bf16_f32 v112, v174, v116
	v_or_b32_e32 v126, 16, v152
	v_lshl_add_u64 v[116:117], v[122:123], 0, v[136:137]
	v_ashrrev_i32_e32 v127, 31, v126
	global_store_dwordx4 v[116:117], v[112:115], off nt
	v_mov_b32_e32 v162, v108
	v_mov_b32_e32 v163, v100
	v_lshlrev_b64 v[112:113], 6, v[126:127]
	v_lshl_add_u64 v[154:155], s[74:75], 0, v[112:113]
	global_load_dwordx4 v[112:115], v[154:155], off
	global_load_dwordx4 v[116:119], v[154:155], off offset:16
	global_load_dwordx4 v[122:125], v[154:155], off offset:32
	s_nop 0
	global_load_dwordx4 v[154:157], v[154:155], off offset:48
	v_mov_b32_e32 v100, v109
	v_mov_b32_e32 v108, v110
	v_mov_b32_e32 v109, v102
	v_mov_b32_e32 v102, v111
	v_mov_b32_e32 v110, v104
	v_mov_b32_e32 v111, v96
	v_mov_b32_e32 v96, v105
	v_mov_b32_e32 v104, v106
	v_mov_b32_e32 v105, v98
	v_mov_b32_e32 v98, v107
	s_waitcnt vmcnt(2)
	v_pk_add_f32 v[112:113], v[112:113], v[114:115]
	v_pk_add_f32 v[116:117], v[116:117], v[118:119]
	s_waitcnt vmcnt(0)
	v_pk_add_f32 v[122:123], v[122:123], v[124:125]
	v_pk_add_f32 v[154:155], v[154:155], v[156:157]
	v_pk_add_f32 v[112:113], v[112:113], v[116:117]
	v_pk_add_f32 v[122:123], v[122:123], v[154:155]
	v_mul_f32_e32 v100, v100, v101
	v_mul_f32_e32 v108, v108, v109
	v_mul_f32_e32 v162, v162, v163
	v_mul_f32_e32 v102, v102, v103
	v_pk_add_f32 v[112:113], v[112:113], v[122:123]
	v_mul_f32_e32 v110, v110, v111
	v_mul_f32_e32 v96, v96, v97
	v_mul_f32_e32 v104, v104, v105
	v_mul_f32_e32 v98, v98, v99
	v_add_f32_e32 v112, v112, v113
	v_fmamk_f32 v112, v112, 0x3a800000, v160
	v_rsq_f32_e32 v113, v112
	s_nop 0
	v_mul_f32_e32 v113, 0xbfb8aa3b, v113
	v_mul_f32_e32 v101, v113, v101
	v_mul_f32_e32 v109, v113, v109
	v_mul_f32_e32 v163, v113, v163
	v_mul_f32_e32 v103, v113, v103
	v_mul_f32_e32 v111, v113, v111
	v_mul_f32_e32 v97, v113, v97
	v_mul_f32_e32 v105, v113, v105
	v_mul_f32_e32 v99, v113, v99
	v_exp_f32_e32 v101, v101
	v_exp_f32_e32 v109, v109
	v_exp_f32_e32 v163, v163
	v_exp_f32_e32 v103, v103
	v_exp_f32_e32 v111, v111
	v_exp_f32_e32 v97, v97
	v_exp_f32_e32 v105, v105
	v_exp_f32_e32 v99, v99
	v_fma_f32 v101, v101, v112, v112
	v_fma_f32 v109, v109, v112, v112
	v_fma_f32 v163, v163, v112, v112
	v_fma_f32 v103, v103, v112, v112
	v_fma_f32 v111, v111, v112, v112
	v_fma_f32 v97, v97, v112, v112
	v_fma_f32 v105, v105, v112, v112
	v_fma_f32 v99, v99, v112, v112
	v_rcp_f32_e32 v101, v101
	v_rcp_f32_e32 v109, v109
	v_rcp_f32_e32 v163, v163
	v_rcp_f32_e32 v103, v103
	v_rcp_f32_e32 v111, v111
	v_rcp_f32_e32 v97, v97
	v_rcp_f32_e32 v105, v105
	v_rcp_f32_e32 v99, v99
	v_mul_f32_e32 v100, v100, v101
	v_mul_f32_e32 v108, v108, v109
	v_mul_f32_e32 v162, v162, v163
	v_mul_f32_e32 v102, v102, v103
	v_mul_f32_e32 v110, v110, v111
	v_mul_f32_e32 v96, v96, v97
	v_mul_f32_e32 v104, v104, v105
	v_mul_f32_e32 v98, v98, v99
	v_cvt_pk_bf16_f32 v97, v108, v102
	v_cvt_pk_bf16_f32 v99, v104, v98
	v_cvt_pk_bf16_f32 v98, v110, v96
	v_cvt_pk_bf16_f32 v96, v162, v100
	v_mad_i64_i32 v[112:113], s[26:27], v126, s51, v[120:121]
	v_lshl_add_u64 v[112:113], v[112:113], 0, s[24:25]
	v_lshl_add_u64 v[100:101], v[112:113], 0, s[6:7]
	v_or_b32_e32 v112, 32, v152
	v_lshl_add_u64 v[100:101], v[100:101], 0, v[136:137]
	v_ashrrev_i32_e32 v113, 31, v112
	global_store_dwordx4 v[100:101], v[96:99], off nt
	v_mov_b32_e32 v114, v92
	v_mov_b32_e32 v92, v94
	v_lshlrev_b64 v[96:97], 6, v[112:113]
	v_lshl_add_u64 v[108:109], s[74:75], 0, v[96:97]
	global_load_dwordx4 v[96:99], v[108:109], off
	global_load_dwordx4 v[100:103], v[108:109], off offset:16
	global_load_dwordx4 v[104:107], v[108:109], off offset:32
	s_nop 0
	global_load_dwordx4 v[108:111], v[108:109], off offset:48
	v_mov_b32_e32 v94, v80
	v_mov_b32_e32 v80, v82
	v_mov_b32_e32 v115, v88
	v_mov_b32_e32 v88, v93
	v_mov_b32_e32 v93, v90
	v_mov_b32_e32 v90, v95
	v_mov_b32_e32 v95, v84
	v_mov_b32_e32 v84, v81
	v_mov_b32_e32 v81, v86
	v_mov_b32_e32 v86, v83
	s_waitcnt vmcnt(2)
	v_pk_add_f32 v[96:97], v[96:97], v[98:99]
	v_pk_add_f32 v[100:101], v[100:101], v[102:103]
	s_waitcnt vmcnt(0)
	v_pk_add_f32 v[104:105], v[104:105], v[106:107]
	v_pk_add_f32 v[108:109], v[108:109], v[110:111]
	v_pk_add_f32 v[96:97], v[96:97], v[100:101]
	v_pk_add_f32 v[104:105], v[104:105], v[108:109]
	v_mul_f32_e32 v114, v114, v115
	v_mul_f32_e32 v88, v88, v89
	v_mul_f32_e32 v92, v92, v93
	v_mul_f32_e32 v90, v90, v91
	v_pk_add_f32 v[96:97], v[96:97], v[104:105]
	v_mul_f32_e32 v94, v94, v95
	v_mul_f32_e32 v84, v84, v85
	v_mul_f32_e32 v80, v80, v81
	v_mul_f32_e32 v86, v86, v87
	v_add_f32_e32 v96, v96, v97
	v_fmamk_f32 v96, v96, 0x3a800000, v160
	v_rsq_f32_e32 v97, v96
	s_nop 0
	v_mul_f32_e32 v97, 0xbfb8aa3b, v97
	v_mul_f32_e32 v115, v97, v115
	v_mul_f32_e32 v89, v97, v89
	v_mul_f32_e32 v93, v97, v93
	v_mul_f32_e32 v91, v97, v91
	v_mul_f32_e32 v95, v97, v95
	v_mul_f32_e32 v85, v97, v85
	v_mul_f32_e32 v81, v97, v81
	v_mul_f32_e32 v87, v97, v87
	v_exp_f32_e32 v115, v115
	v_exp_f32_e32 v89, v89
	v_exp_f32_e32 v93, v93
	v_exp_f32_e32 v91, v91
	v_exp_f32_e32 v95, v95
	v_exp_f32_e32 v85, v85
	v_exp_f32_e32 v81, v81
	v_exp_f32_e32 v87, v87
	v_fma_f32 v115, v115, v96, v96
	v_fma_f32 v89, v89, v96, v96
	v_fma_f32 v93, v93, v96, v96
	v_fma_f32 v91, v91, v96, v96
	v_fma_f32 v95, v95, v96, v96
	v_fma_f32 v85, v85, v96, v96
	v_fma_f32 v81, v81, v96, v96
	v_fma_f32 v87, v87, v96, v96
	v_rcp_f32_e32 v115, v115
	v_rcp_f32_e32 v89, v89
	v_rcp_f32_e32 v93, v93
	v_rcp_f32_e32 v91, v91
	v_rcp_f32_e32 v95, v95
	v_rcp_f32_e32 v85, v85
	v_rcp_f32_e32 v81, v81
	v_rcp_f32_e32 v87, v87
	v_mul_f32_e32 v114, v114, v115
	v_mul_f32_e32 v88, v88, v89
	v_mul_f32_e32 v92, v92, v93
	v_mul_f32_e32 v90, v90, v91
	v_mul_f32_e32 v94, v94, v95
	v_mul_f32_e32 v84, v84, v85
	v_mul_f32_e32 v80, v80, v81
	v_mul_f32_e32 v86, v86, v87
	v_cvt_pk_bf16_f32 v81, v92, v90
	v_cvt_pk_bf16_f32 v82, v94, v84
	v_cvt_pk_bf16_f32 v83, v80, v86
	v_cvt_pk_bf16_f32 v80, v114, v88
	v_mad_i64_i32 v[96:97], s[26:27], v112, s51, v[120:121]
	v_lshl_add_u64 v[84:85], v[96:97], 0, s[24:25]
	v_lshl_add_u64 v[84:85], v[84:85], 0, s[6:7]
	v_or_b32_e32 v96, 48, v152
	v_lshl_add_u64 v[84:85], v[84:85], 0, v[136:137]
	v_ashrrev_i32_e32 v97, 31, v96
	global_store_dwordx4 v[84:85], v[80:83], off nt
	v_mov_b32_e32 v98, v76
	v_mov_b32_e32 v99, v72
	v_lshlrev_b64 v[80:81], 6, v[96:97]
	v_lshl_add_u64 v[92:93], s[74:75], 0, v[80:81]
	global_load_dwordx4 v[80:83], v[92:93], off
	global_load_dwordx4 v[84:87], v[92:93], off offset:16
	global_load_dwordx4 v[88:91], v[92:93], off offset:32
	s_nop 0
	global_load_dwordx4 v[92:95], v[92:93], off offset:48
	v_mov_b32_e32 v72, v77
	v_mov_b32_e32 v76, v78
	v_mov_b32_e32 v77, v74
	v_mov_b32_e32 v74, v79
	v_mov_b32_e32 v78, v64
	v_mov_b32_e32 v79, v68
	v_mov_b32_e32 v68, v65
	s_waitcnt vmcnt(2)
	v_pk_add_f32 v[80:81], v[80:81], v[82:83]
	v_pk_add_f32 v[84:85], v[84:85], v[86:87]
	s_waitcnt vmcnt(0)
	v_pk_add_f32 v[88:89], v[88:89], v[90:91]
	v_pk_add_f32 v[92:93], v[92:93], v[94:95]
	v_pk_add_f32 v[80:81], v[80:81], v[84:85]
	v_pk_add_f32 v[88:89], v[88:89], v[92:93]
	v_mul_f32_e32 v98, v98, v99
	v_mul_f32_e32 v72, v72, v73
	v_mul_f32_e32 v76, v76, v77
	v_mul_f32_e32 v68, v68, v69
	v_pk_add_f32 v[80:81], v[80:81], v[88:89]
	v_mul_f32_e32 v66, v66, v70
	v_mul_f32_e32 v74, v74, v75
	v_mul_f32_e32 v78, v78, v79
	v_mul_f32_e32 v67, v67, v71
	v_add_f32_e32 v80, v80, v81
	v_fmamk_f32 v80, v80, 0x3a800000, v160
	v_rsq_f32_e32 v81, v80
	s_nop 0
	v_mul_f32_e32 v81, 0xbfb8aa3b, v81
	v_mul_f32_e32 v99, v81, v99
	v_mul_f32_e32 v73, v81, v73
	v_mul_f32_e32 v77, v81, v77
	v_mul_f32_e32 v69, v81, v69
	v_mul_f32_e32 v70, v81, v70
	v_mul_f32_e32 v75, v81, v75
	v_mul_f32_e32 v79, v81, v79
	v_mul_f32_e32 v71, v81, v71
	v_exp_f32_e32 v99, v99
	v_exp_f32_e32 v73, v73
	v_exp_f32_e32 v77, v77
	v_exp_f32_e32 v69, v69
	v_exp_f32_e32 v70, v70
	v_exp_f32_e32 v75, v75
	v_exp_f32_e32 v79, v79
	v_exp_f32_e32 v71, v71
	v_fma_f32 v99, v99, v80, v80
	v_fma_f32 v73, v73, v80, v80
	v_fma_f32 v77, v77, v80, v80
	v_fma_f32 v69, v69, v80, v80
	v_fma_f32 v70, v70, v80, v80
	v_fma_f32 v75, v75, v80, v80
	v_fma_f32 v79, v79, v80, v80
	v_fma_f32 v71, v71, v80, v80
	v_rcp_f32_e32 v99, v99
	v_rcp_f32_e32 v73, v73
	v_rcp_f32_e32 v77, v77
	v_rcp_f32_e32 v69, v69
	v_rcp_f32_e32 v70, v70
	v_rcp_f32_e32 v75, v75
	v_rcp_f32_e32 v79, v79
	v_rcp_f32_e32 v71, v71
	v_mul_f32_e32 v98, v98, v99
	v_mul_f32_e32 v72, v72, v73
	v_mul_f32_e32 v76, v76, v77
	v_mul_f32_e32 v68, v68, v69
	v_mul_f32_e32 v66, v66, v70
	v_mul_f32_e32 v74, v74, v75
	v_mul_f32_e32 v78, v78, v79
	v_mul_f32_e32 v67, v67, v71
	v_cvt_pk_bf16_f32 v64, v98, v72
	v_cvt_pk_bf16_f32 v65, v76, v74
	v_cvt_pk_bf16_f32 v67, v66, v67
	v_cvt_pk_bf16_f32 v66, v78, v68
	v_mad_i64_i32 v[68:69], s[26:27], v96, s51, v[120:121]
	v_lshl_add_u64 v[68:69], v[68:69], 0, s[24:25]
	v_lshl_add_u64 v[68:69], v[68:69], 0, s[6:7]
	v_add_u32_e32 v80, 0x80, v152
	v_lshl_add_u64 v[68:69], v[68:69], 0, v[136:137]
	v_ashrrev_i32_e32 v81, 31, v80
	global_store_dwordx4 v[68:69], v[64:67], off nt
	v_mov_b32_e32 v82, v60
	v_mov_b32_e32 v83, v56
	v_lshlrev_b64 v[64:65], 6, v[80:81]
	v_lshl_add_u64 v[76:77], s[74:75], 0, v[64:65]
	global_load_dwordx4 v[64:67], v[76:77], off
	global_load_dwordx4 v[68:71], v[76:77], off offset:16
	global_load_dwordx4 v[72:75], v[76:77], off offset:32
	s_nop 0
	global_load_dwordx4 v[76:79], v[76:77], off offset:48
	v_mov_b32_e32 v56, v61
	v_mov_b32_e32 v60, v62
	v_mov_b32_e32 v61, v58
	v_mov_b32_e32 v58, v63
	v_mov_b32_e32 v62, v48
	v_mov_b32_e32 v63, v52
	v_mov_b32_e32 v52, v49
	s_waitcnt vmcnt(2)
	v_pk_add_f32 v[64:65], v[64:65], v[66:67]
	v_pk_add_f32 v[68:69], v[68:69], v[70:71]
	s_waitcnt vmcnt(0)
	v_pk_add_f32 v[72:73], v[72:73], v[74:75]
	v_pk_add_f32 v[76:77], v[76:77], v[78:79]
	v_pk_add_f32 v[64:65], v[64:65], v[68:69]
	v_pk_add_f32 v[72:73], v[72:73], v[76:77]
	v_mul_f32_e32 v82, v82, v83
	v_mul_f32_e32 v56, v56, v57
	v_mul_f32_e32 v60, v60, v61
	v_mul_f32_e32 v52, v52, v53
	v_pk_add_f32 v[64:65], v[64:65], v[72:73]
	v_mul_f32_e32 v50, v50, v54
	v_mul_f32_e32 v58, v58, v59
	v_mul_f32_e32 v62, v62, v63
	v_mul_f32_e32 v51, v51, v55
	v_add_f32_e32 v64, v64, v65
	v_fmamk_f32 v64, v64, 0x3a800000, v160
	v_rsq_f32_e32 v65, v64
	s_nop 0
	v_mul_f32_e32 v65, 0xbfb8aa3b, v65
	v_mul_f32_e32 v83, v65, v83
	v_mul_f32_e32 v57, v65, v57
	v_mul_f32_e32 v61, v65, v61
	v_mul_f32_e32 v53, v65, v53
	v_mul_f32_e32 v54, v65, v54
	v_mul_f32_e32 v59, v65, v59
	v_mul_f32_e32 v63, v65, v63
	v_mul_f32_e32 v55, v65, v55
	v_exp_f32_e32 v83, v83
	v_exp_f32_e32 v57, v57
	v_exp_f32_e32 v61, v61
	v_exp_f32_e32 v53, v53
	v_exp_f32_e32 v54, v54
	v_exp_f32_e32 v59, v59
	v_exp_f32_e32 v63, v63
	v_exp_f32_e32 v55, v55
	v_fma_f32 v83, v83, v64, v64
	v_fma_f32 v57, v57, v64, v64
	v_fma_f32 v61, v61, v64, v64
	v_fma_f32 v53, v53, v64, v64
	v_fma_f32 v54, v54, v64, v64
	v_fma_f32 v59, v59, v64, v64
	v_fma_f32 v63, v63, v64, v64
	v_fma_f32 v55, v55, v64, v64
	v_rcp_f32_e32 v83, v83
	v_rcp_f32_e32 v57, v57
	v_rcp_f32_e32 v61, v61
	v_rcp_f32_e32 v53, v53
	v_rcp_f32_e32 v54, v54
	v_rcp_f32_e32 v59, v59
	v_rcp_f32_e32 v63, v63
	v_rcp_f32_e32 v55, v55
	v_mul_f32_e32 v82, v82, v83
	v_mul_f32_e32 v56, v56, v57
	v_mul_f32_e32 v60, v60, v61
	v_mul_f32_e32 v52, v52, v53
	v_mul_f32_e32 v50, v50, v54
	v_mul_f32_e32 v58, v58, v59
	v_mul_f32_e32 v62, v62, v63
	v_mul_f32_e32 v51, v51, v55
	v_cvt_pk_bf16_f32 v48, v82, v56
	v_cvt_pk_bf16_f32 v49, v60, v58
	v_cvt_pk_bf16_f32 v51, v50, v51
	v_cvt_pk_bf16_f32 v50, v62, v52
	v_mad_i64_i32 v[52:53], s[26:27], v80, s51, v[120:121]
	v_lshl_add_u64 v[52:53], v[52:53], 0, s[24:25]
	v_lshl_add_u64 v[52:53], v[52:53], 0, s[6:7]
	v_add_u32_e32 v64, 0x90, v152
	v_lshl_add_u64 v[52:53], v[52:53], 0, v[136:137]
	v_ashrrev_i32_e32 v65, 31, v64
	global_store_dwordx4 v[52:53], v[48:51], off nt
	v_mov_b32_e32 v66, v44
	v_mov_b32_e32 v67, v40
	v_lshlrev_b64 v[48:49], 6, v[64:65]
	v_lshl_add_u64 v[60:61], s[74:75], 0, v[48:49]
	global_load_dwordx4 v[48:51], v[60:61], off
	global_load_dwordx4 v[52:55], v[60:61], off offset:16
	global_load_dwordx4 v[56:59], v[60:61], off offset:32
	s_nop 0
	global_load_dwordx4 v[60:63], v[60:61], off offset:48
	v_mov_b32_e32 v40, v45
	v_mov_b32_e32 v44, v46
	v_mov_b32_e32 v45, v42
	v_mov_b32_e32 v42, v47
	v_mov_b32_e32 v46, v32
	v_mov_b32_e32 v47, v36
	v_mov_b32_e32 v36, v33
	s_waitcnt vmcnt(2)
	v_pk_add_f32 v[48:49], v[48:49], v[50:51]
	v_pk_add_f32 v[52:53], v[52:53], v[54:55]
	s_waitcnt vmcnt(0)
	v_pk_add_f32 v[56:57], v[56:57], v[58:59]
	v_pk_add_f32 v[60:61], v[60:61], v[62:63]
	v_pk_add_f32 v[48:49], v[48:49], v[52:53]
	v_pk_add_f32 v[56:57], v[56:57], v[60:61]
	v_mul_f32_e32 v66, v66, v67
	v_mul_f32_e32 v40, v40, v41
	v_mul_f32_e32 v44, v44, v45
	v_mul_f32_e32 v36, v36, v37
	v_pk_add_f32 v[48:49], v[48:49], v[56:57]
	v_mul_f32_e32 v34, v34, v38
	v_mul_f32_e32 v42, v42, v43
	v_mul_f32_e32 v46, v46, v47
	v_mul_f32_e32 v35, v35, v39
	v_add_f32_e32 v48, v48, v49
	v_fmamk_f32 v48, v48, 0x3a800000, v160
	v_rsq_f32_e32 v49, v48
	s_nop 0
	v_mul_f32_e32 v49, 0xbfb8aa3b, v49
	v_mul_f32_e32 v67, v49, v67
	v_mul_f32_e32 v41, v49, v41
	v_mul_f32_e32 v45, v49, v45
	v_mul_f32_e32 v37, v49, v37
	v_mul_f32_e32 v38, v49, v38
	v_mul_f32_e32 v43, v49, v43
	v_mul_f32_e32 v47, v49, v47
	v_mul_f32_e32 v39, v49, v39
	v_exp_f32_e32 v67, v67
	v_exp_f32_e32 v41, v41
	v_exp_f32_e32 v45, v45
	v_exp_f32_e32 v37, v37
	v_exp_f32_e32 v38, v38
	v_exp_f32_e32 v43, v43
	v_exp_f32_e32 v47, v47
	v_exp_f32_e32 v39, v39
	v_fma_f32 v67, v67, v48, v48
	v_fma_f32 v41, v41, v48, v48
	v_fma_f32 v45, v45, v48, v48
	v_fma_f32 v37, v37, v48, v48
	v_fma_f32 v38, v38, v48, v48
	v_fma_f32 v43, v43, v48, v48
	v_fma_f32 v47, v47, v48, v48
	v_fma_f32 v39, v39, v48, v48
	v_rcp_f32_e32 v67, v67
	v_rcp_f32_e32 v41, v41
	v_rcp_f32_e32 v45, v45
	v_rcp_f32_e32 v37, v37
	v_rcp_f32_e32 v38, v38
	v_rcp_f32_e32 v43, v43
	v_rcp_f32_e32 v47, v47
	v_rcp_f32_e32 v39, v39
	v_mul_f32_e32 v66, v66, v67
	v_mul_f32_e32 v40, v40, v41
	v_mul_f32_e32 v44, v44, v45
	v_mul_f32_e32 v36, v36, v37
	v_mul_f32_e32 v34, v34, v38
	v_mul_f32_e32 v42, v42, v43
	v_mul_f32_e32 v46, v46, v47
	v_mul_f32_e32 v35, v35, v39
	v_cvt_pk_bf16_f32 v32, v66, v40
	v_cvt_pk_bf16_f32 v33, v44, v42
	v_cvt_pk_bf16_f32 v35, v34, v35
	v_cvt_pk_bf16_f32 v34, v46, v36
	v_mad_i64_i32 v[36:37], s[26:27], v64, s51, v[120:121]
	v_lshl_add_u64 v[36:37], v[36:37], 0, s[24:25]
	v_lshl_add_u64 v[36:37], v[36:37], 0, s[6:7]
	v_add_u32_e32 v48, 0xa0, v152
	v_lshl_add_u64 v[36:37], v[36:37], 0, v[136:137]
	v_ashrrev_i32_e32 v49, 31, v48
	global_store_dwordx4 v[36:37], v[32:35], off nt
	v_mov_b32_e32 v50, v28
	v_mov_b32_e32 v51, v24
	v_lshlrev_b64 v[32:33], 6, v[48:49]
	v_lshl_add_u64 v[44:45], s[74:75], 0, v[32:33]
	global_load_dwordx4 v[32:35], v[44:45], off
	global_load_dwordx4 v[36:39], v[44:45], off offset:16
	global_load_dwordx4 v[40:43], v[44:45], off offset:32
	s_nop 0
	global_load_dwordx4 v[44:47], v[44:45], off offset:48
	v_mov_b32_e32 v24, v29
	v_mov_b32_e32 v28, v30
	v_mov_b32_e32 v29, v26
	v_mov_b32_e32 v26, v31
	v_mov_b32_e32 v30, v16
	v_mov_b32_e32 v31, v20
	v_mov_b32_e32 v20, v17
	s_waitcnt vmcnt(2)
	v_pk_add_f32 v[32:33], v[32:33], v[34:35]
	v_pk_add_f32 v[36:37], v[36:37], v[38:39]
	s_waitcnt vmcnt(0)
	v_pk_add_f32 v[40:41], v[40:41], v[42:43]
	v_pk_add_f32 v[44:45], v[44:45], v[46:47]
	v_pk_add_f32 v[32:33], v[32:33], v[36:37]
	v_pk_add_f32 v[40:41], v[40:41], v[44:45]
	v_mul_f32_e32 v50, v50, v51
	v_mul_f32_e32 v24, v24, v25
	v_mul_f32_e32 v28, v28, v29
	v_mul_f32_e32 v20, v20, v21
	v_pk_add_f32 v[32:33], v[32:33], v[40:41]
	v_mul_f32_e32 v18, v18, v22
	v_mul_f32_e32 v26, v26, v27
	v_mul_f32_e32 v30, v30, v31
	v_mul_f32_e32 v19, v19, v23
	v_add_f32_e32 v32, v32, v33
	v_fmamk_f32 v32, v32, 0x3a800000, v160
	v_rsq_f32_e32 v33, v32
	s_nop 0
	v_mul_f32_e32 v33, 0xbfb8aa3b, v33
	v_mul_f32_e32 v51, v33, v51
	v_mul_f32_e32 v25, v33, v25
	v_mul_f32_e32 v29, v33, v29
	v_mul_f32_e32 v21, v33, v21
	v_mul_f32_e32 v22, v33, v22
	v_mul_f32_e32 v27, v33, v27
	v_mul_f32_e32 v31, v33, v31
	v_mul_f32_e32 v23, v33, v23
	v_exp_f32_e32 v51, v51
	v_exp_f32_e32 v25, v25
	v_exp_f32_e32 v29, v29
	v_exp_f32_e32 v21, v21
	v_exp_f32_e32 v22, v22
	v_exp_f32_e32 v27, v27
	v_exp_f32_e32 v31, v31
	v_exp_f32_e32 v23, v23
	v_fma_f32 v51, v51, v32, v32
	v_fma_f32 v25, v25, v32, v32
	v_fma_f32 v29, v29, v32, v32
	v_fma_f32 v21, v21, v32, v32
	v_fma_f32 v22, v22, v32, v32
	v_fma_f32 v27, v27, v32, v32
	v_fma_f32 v31, v31, v32, v32
	v_fma_f32 v23, v23, v32, v32
	v_rcp_f32_e32 v51, v51
	v_rcp_f32_e32 v25, v25
	v_rcp_f32_e32 v29, v29
	v_rcp_f32_e32 v21, v21
	v_rcp_f32_e32 v22, v22
	v_rcp_f32_e32 v27, v27
	v_rcp_f32_e32 v31, v31
	v_rcp_f32_e32 v23, v23
	v_mul_f32_e32 v50, v50, v51
	v_mul_f32_e32 v24, v24, v25
	v_mul_f32_e32 v28, v28, v29
	v_mul_f32_e32 v20, v20, v21
	v_mul_f32_e32 v18, v18, v22
	v_mul_f32_e32 v26, v26, v27
	v_mul_f32_e32 v30, v30, v31
	v_mul_f32_e32 v19, v19, v23
	v_cvt_pk_bf16_f32 v16, v50, v24
	v_cvt_pk_bf16_f32 v17, v28, v26
	v_cvt_pk_bf16_f32 v19, v18, v19
	v_cvt_pk_bf16_f32 v18, v30, v20
	v_mad_i64_i32 v[20:21], s[26:27], v48, s51, v[120:121]
	v_lshl_add_u64 v[20:21], v[20:21], 0, s[24:25]
	v_lshl_add_u64 v[20:21], v[20:21], 0, s[6:7]
	v_add_u32_e32 v32, 0xb0, v152
	v_lshl_add_u64 v[20:21], v[20:21], 0, v[136:137]
	v_ashrrev_i32_e32 v33, 31, v32
	global_store_dwordx4 v[20:21], v[16:19], off nt
	v_mov_b32_e32 v34, v12
	v_mov_b32_e32 v35, v8
	v_lshlrev_b64 v[16:17], 6, v[32:33]
	v_lshl_add_u64 v[28:29], s[74:75], 0, v[16:17]
	global_load_dwordx4 v[16:19], v[28:29], off
	global_load_dwordx4 v[20:23], v[28:29], off offset:16
	global_load_dwordx4 v[24:27], v[28:29], off offset:32
	s_nop 0
	global_load_dwordx4 v[28:31], v[28:29], off offset:48
	v_mov_b32_e32 v8, v13
	v_mov_b32_e32 v12, v14
	v_mov_b32_e32 v13, v10
	v_mov_b32_e32 v10, v15
	v_mov_b32_e32 v14, v0
	v_mov_b32_e32 v15, v4
	v_mov_b32_e32 v4, v1
	s_waitcnt vmcnt(2)
	v_pk_add_f32 v[16:17], v[16:17], v[18:19]
	v_pk_add_f32 v[20:21], v[20:21], v[22:23]
	s_waitcnt vmcnt(0)
	v_pk_add_f32 v[24:25], v[24:25], v[26:27]
	v_pk_add_f32 v[28:29], v[28:29], v[30:31]
	v_pk_add_f32 v[16:17], v[16:17], v[20:21]
	v_pk_add_f32 v[24:25], v[24:25], v[28:29]
	v_mul_f32_e32 v34, v34, v35
	v_mul_f32_e32 v8, v8, v9
	v_mul_f32_e32 v12, v12, v13
	v_mul_f32_e32 v4, v4, v5
	v_pk_add_f32 v[16:17], v[16:17], v[24:25]
	v_mul_f32_e32 v2, v2, v6
	v_mul_f32_e32 v10, v10, v11
	v_mul_f32_e32 v14, v14, v15
	v_mul_f32_e32 v3, v3, v7
	v_add_f32_e32 v16, v16, v17
	v_fmamk_f32 v16, v16, 0x3a800000, v160
	v_rsq_f32_e32 v17, v16
	s_nop 0
	v_mul_f32_e32 v17, 0xbfb8aa3b, v17
	v_mul_f32_e32 v35, v17, v35
	v_mul_f32_e32 v9, v17, v9
	v_mul_f32_e32 v13, v17, v13
	v_mul_f32_e32 v5, v17, v5
	v_mul_f32_e32 v6, v17, v6
	v_mul_f32_e32 v11, v17, v11
	v_mul_f32_e32 v15, v17, v15
	v_mul_f32_e32 v7, v17, v7
	v_exp_f32_e32 v35, v35
	v_exp_f32_e32 v9, v9
	v_exp_f32_e32 v13, v13
	v_exp_f32_e32 v5, v5
	v_exp_f32_e32 v6, v6
	v_exp_f32_e32 v11, v11
	v_exp_f32_e32 v15, v15
	v_exp_f32_e32 v7, v7
	v_fma_f32 v35, v35, v16, v16
	v_fma_f32 v9, v9, v16, v16
	v_fma_f32 v13, v13, v16, v16
	v_fma_f32 v5, v5, v16, v16
	v_fma_f32 v6, v6, v16, v16
	v_fma_f32 v11, v11, v16, v16
	v_fma_f32 v15, v15, v16, v16
	v_fma_f32 v7, v7, v16, v16
	v_rcp_f32_e32 v35, v35
	v_rcp_f32_e32 v9, v9
	v_rcp_f32_e32 v13, v13
	v_rcp_f32_e32 v5, v5
	v_rcp_f32_e32 v6, v6
	v_rcp_f32_e32 v11, v11
	v_rcp_f32_e32 v15, v15
	v_rcp_f32_e32 v7, v7
	v_mul_f32_e32 v34, v34, v35
	v_mul_f32_e32 v8, v8, v9
	v_mul_f32_e32 v12, v12, v13
	v_mul_f32_e32 v4, v4, v5
	v_mul_f32_e32 v2, v2, v6
	v_mul_f32_e32 v10, v10, v11
	v_mul_f32_e32 v14, v14, v15
	v_mul_f32_e32 v3, v3, v7
	v_cvt_pk_bf16_f32 v0, v34, v8
	v_cvt_pk_bf16_f32 v1, v12, v10
	v_cvt_pk_bf16_f32 v3, v2, v3
	v_cvt_pk_bf16_f32 v2, v14, v4
	v_mad_i64_i32 v[4:5], s[26:27], v32, s51, v[120:121]
	v_lshl_add_u64 v[4:5], v[4:5], 0, s[24:25]
	v_lshl_add_u64 v[4:5], v[4:5], 0, s[6:7]
	v_lshl_add_u64 v[4:5], v[4:5], 0, v[136:137]
	global_store_dwordx4 v[4:5], v[0:3], off nt
	s_andn2_b64 vcc, exec, s[4:5]
	s_mov_b64 s[4:5], -1
	s_cbranch_vccnz .LBB0_157
	s_branch .LBB0_191

.LBB0_362:
	s_and_b64 vcc, exec, s[2:3]
	s_cbranch_vccz .LBB0_361
	v_ashrrev_i32_e32 v151, 31, v150
	v_lshlrev_b64 v[128:129], 11, v[150:151]
	v_lshl_add_u64 v[128:129], s[8:9], 0, v[128:129]
	v_lshl_or_b32 v140, s80, 9, v142
	v_lshl_add_u64 v[128:129], v[128:129], 0, v[140:141]
	v_cvt_pk_bf16_f32 v124, v124, v125
	v_cvt_pk_bf16_f32 v125, v126, v127
	v_cvt_pk_bf16_f32 v126, v120, v121
	v_cvt_pk_bf16_f32 v127, v122, v123
	global_store_dwordx4 v[128:129], v[124:127], off nt
	v_cvt_pk_bf16_f32 v112, v112, v113
	v_cvt_pk_bf16_f32 v113, v114, v115
	v_cvt_pk_bf16_f32 v114, v104, v105
	v_or_b32_e32 v104, 16, v150
	v_ashrrev_i32_e32 v105, 31, v104
	v_lshlrev_b64 v[104:105], 11, v[104:105]
	v_lshl_add_u64 v[104:105], s[8:9], 0, v[104:105]
	v_cvt_pk_bf16_f32 v115, v106, v107
	global_store_dwordx4 v[128:129], v[112:115], off offset:256
	v_lshl_add_u64 v[152:153], v[128:129], 0, s[30:31]
	s_nop 0
	v_lshl_add_u64 v[112:113], v[104:105], 0, v[140:141]
	v_cvt_pk_bf16_f32 v104, v116, v117
	v_cvt_pk_bf16_f32 v105, v118, v119
	v_cvt_pk_bf16_f32 v106, v108, v109
	v_cvt_pk_bf16_f32 v107, v110, v111
	global_store_dwordx4 v[112:113], v[104:107], off
	v_cvt_pk_bf16_f32 v96, v96, v97
	v_cvt_pk_bf16_f32 v97, v98, v99
	v_cvt_pk_bf16_f32 v98, v88, v89
	v_or_b32_e32 v88, 32, v150
	v_ashrrev_i32_e32 v89, 31, v88
	v_lshlrev_b64 v[88:89], 11, v[88:89]
	v_lshl_add_u64 v[88:89], s[8:9], 0, v[88:89]
	v_cvt_pk_bf16_f32 v99, v90, v91
	global_store_dwordx4 v[112:113], v[96:99], off offset:256
	s_nop 1
	v_lshl_add_u64 v[96:97], v[88:89], 0, v[140:141]
	v_cvt_pk_bf16_f32 v88, v100, v101
	v_cvt_pk_bf16_f32 v89, v102, v103
	v_cvt_pk_bf16_f32 v90, v92, v93
	v_cvt_pk_bf16_f32 v91, v94, v95
	global_store_dwordx4 v[96:97], v[88:91], off
	v_cvt_pk_bf16_f32 v80, v80, v81
	v_cvt_pk_bf16_f32 v81, v82, v83
	v_cvt_pk_bf16_f32 v82, v72, v73
	v_or_b32_e32 v72, 48, v150
	v_ashrrev_i32_e32 v73, 31, v72
	v_lshlrev_b64 v[72:73], 11, v[72:73]
	v_lshl_add_u64 v[72:73], s[8:9], 0, v[72:73]
	v_cvt_pk_bf16_f32 v83, v74, v75
	global_store_dwordx4 v[96:97], v[80:83], off offset:256
	s_nop 1
	v_lshl_add_u64 v[80:81], v[72:73], 0, v[140:141]
	v_cvt_pk_bf16_f32 v72, v84, v85
	v_cvt_pk_bf16_f32 v73, v86, v87
	v_cvt_pk_bf16_f32 v74, v76, v77
	v_cvt_pk_bf16_f32 v75, v78, v79
	global_store_dwordx4 v[80:81], v[72:75], off
	v_cvt_pk_bf16_f32 v68, v68, v69
	v_cvt_pk_bf16_f32 v69, v70, v71
	v_cvt_pk_bf16_f32 v70, v64, v65
	v_cvt_pk_bf16_f32 v71, v66, v67
	global_store_dwordx4 v[80:81], v[68:71], off offset:256
	v_cvt_pk_bf16_f32 v60, v60, v61
	v_cvt_pk_bf16_f32 v61, v62, v63
	v_cvt_pk_bf16_f32 v62, v56, v57
	v_add_co_u32_e32 v56, vcc, s67, v128
	v_lshl_add_u64 v[64:65], v[128:129], 0, s[24:25]
	s_nop 0
	v_addc_co_u32_e32 v57, vcc, 0, v129, vcc
	v_cvt_pk_bf16_f32 v63, v58, v59
	global_store_dwordx4 v[56:57], v[60:63], off
	v_cvt_pk_bf16_f32 v48, v48, v49
	v_cvt_pk_bf16_f32 v49, v50, v51
	v_cvt_pk_bf16_f32 v50, v40, v41
	v_cvt_pk_bf16_f32 v51, v42, v43
	global_store_dwordx4 v[64:65], v[48:51], off offset:256
	v_cvt_pk_bf16_f32 v40, v52, v53
	v_cvt_pk_bf16_f32 v41, v54, v55
	v_cvt_pk_bf16_f32 v42, v44, v45
	v_add_co_u32_e32 v44, vcc, s68, v128
	s_nop 0
	v_lshl_add_u64 v[48:49], v[128:129], 0, s[26:27]
	v_addc_co_u32_e32 v45, vcc, 0, v129, vcc
	v_cvt_pk_bf16_f32 v43, v46, v47
	global_store_dwordx4 v[44:45], v[40:43], off
	v_cvt_pk_bf16_f32 v32, v32, v33
	v_cvt_pk_bf16_f32 v33, v34, v35
	v_cvt_pk_bf16_f32 v34, v24, v25
	v_cvt_pk_bf16_f32 v35, v26, v27
	global_store_dwordx4 v[48:49], v[32:35], off offset:256
	v_cvt_pk_bf16_f32 v24, v36, v37
	v_cvt_pk_bf16_f32 v25, v38, v39
	v_cvt_pk_bf16_f32 v26, v28, v29
	v_add_co_u32_e32 v28, vcc, s69, v128
	s_nop 0
	v_lshl_add_u64 v[32:33], v[128:129], 0, s[28:29]
	v_addc_co_u32_e32 v29, vcc, 0, v129, vcc
	v_cvt_pk_bf16_f32 v27, v30, v31
	global_store_dwordx4 v[28:29], v[24:27], off
	v_cvt_pk_bf16_f32 v16, v16, v17
	v_cvt_pk_bf16_f32 v17, v18, v19
	v_cvt_pk_bf16_f32 v18, v8, v9
	v_cvt_pk_bf16_f32 v19, v10, v11
	global_store_dwordx4 v[32:33], v[16:19], off offset:256
	v_cvt_pk_bf16_f32 v8, v20, v21
	v_cvt_pk_bf16_f32 v9, v22, v23
	v_cvt_pk_bf16_f32 v10, v12, v13
	v_add_co_u32_e32 v12, vcc, s78, v128
	v_cvt_pk_bf16_f32 v11, v14, v15
	s_nop 1
	v_addc_co_u32_e32 v13, vcc, 0, v129, vcc
	global_store_dwordx4 v[12:13], v[8:11], off
	v_cvt_pk_bf16_f32 v128, v4, v5
	v_cvt_pk_bf16_f32 v129, v6, v7
	v_cvt_pk_bf16_f32 v130, v0, v1
	v_cvt_pk_bf16_f32 v131, v2, v3
	s_andn2_b64 vcc, exec, s[40:41]
	s_mov_b64 s[2:3], -1
	global_store_dwordx4 v[152:153], v[128:131], off offset:256
	s_cbranch_vccnz .LBB0_330

.LBB0_473:
	v_or_b32_e32 v112, 16, v146
	v_ashrrev_i32_e32 v113, 31, v112
	v_lshlrev_b64 v[112:113], 11, v[112:113]
	v_lshl_add_u64 v[112:113], v[148:149], 0, v[112:113]
	s_and_b64 vcc, exec, s[4:5]
	v_cvt_pk_bf16_f32 v108, v108, v109
	v_cvt_pk_bf16_f32 v109, v110, v111
	v_cvt_pk_bf16_f32 v110, v104, v105
	v_cvt_pk_bf16_f32 v111, v106, v107
	global_store_dwordx4 v[112:113], v[108:111], off nt
	s_cbranch_vccnz .LBB0_475
	global_load_dwordx4 v[104:107], v[144:145], off offset:512
	global_load_dwordx4 v[108:111], v[144:145], off offset:528
	s_waitcnt vmcnt(0)
	v_pk_add_f32 v[102:103], v[102:103], v[106:107]
	v_pk_add_f32 v[100:101], v[100:101], v[104:105]
	v_pk_add_f32 v[98:99], v[98:99], v[110:111]
	v_pk_add_f32 v[96:97], v[96:97], v[108:109]
	v_mul_f32_e32 v100, 0xbfb8aa3b, v100
	v_mul_f32_e32 v96, 0xbfb8aa3b, v96
	v_mul_f32_e32 v101, 0xbfb8aa3b, v101
	v_mul_f32_e32 v97, 0xbfb8aa3b, v97
	v_mul_f32_e32 v102, 0xbfb8aa3b, v102
	v_mul_f32_e32 v98, 0xbfb8aa3b, v98
	v_mul_f32_e32 v103, 0xbfb8aa3b, v103
	v_mul_f32_e32 v99, 0xbfb8aa3b, v99
	v_exp_f32_e32 v100, v100
	v_exp_f32_e32 v96, v96
	v_exp_f32_e32 v101, v101
	v_exp_f32_e32 v97, v97
	v_exp_f32_e32 v102, v102
	v_exp_f32_e32 v98, v98
	v_exp_f32_e32 v103, v103
	v_exp_f32_e32 v99, v99
	v_add_f32_e32 v100, 1.0, v100
	v_add_f32_e32 v104, 1.0, v96
	v_add_f32_e32 v101, 1.0, v101
	v_add_f32_e32 v105, 1.0, v97
	v_add_f32_e32 v102, 1.0, v102
	v_add_f32_e32 v106, 1.0, v98
	v_add_f32_e32 v103, 1.0, v103
	v_add_f32_e32 v107, 1.0, v99
	v_rcp_f32_e32 v96, v100
	v_rcp_f32_e32 v104, v104
	v_rcp_f32_e32 v97, v101
	v_rcp_f32_e32 v98, v102
	v_rcp_f32_e32 v99, v103
	v_rcp_f32_e32 v106, v106
	v_rcp_f32_e32 v107, v107
	v_rcp_f32_e32 v105, v105
	v_pk_mul_f32 v[102:103], v[142:143], v[98:99] op_sel_hi:[0,1]
	v_pk_mul_f32 v[100:101], v[142:143], v[96:97] op_sel_hi:[0,1]
	v_pk_mul_f32 v[98:99], v[142:143], v[106:107] op_sel_hi:[0,1]
	v_pk_mul_f32 v[96:97], v[142:143], v[104:105] op_sel_hi:[0,1]

.LBB0_477:
	v_or_b32_e32 v96, 32, v146
	v_ashrrev_i32_e32 v97, 31, v96
	v_lshlrev_b64 v[96:97], 11, v[96:97]
	v_lshl_add_u64 v[96:97], v[148:149], 0, v[96:97]
	s_and_b64 vcc, exec, s[4:5]
	v_cvt_pk_bf16_f32 v92, v92, v93
	v_cvt_pk_bf16_f32 v93, v94, v95
	v_cvt_pk_bf16_f32 v94, v88, v89
	v_cvt_pk_bf16_f32 v95, v90, v91
	global_store_dwordx4 v[96:97], v[92:95], off nt
	s_cbranch_vccnz .LBB0_479
	global_load_dwordx4 v[88:91], v[144:145], off offset:512
	global_load_dwordx4 v[92:95], v[144:145], off offset:528
	s_waitcnt vmcnt(0)
	v_pk_add_f32 v[86:87], v[86:87], v[90:91]
	v_pk_add_f32 v[84:85], v[84:85], v[88:89]
	v_pk_add_f32 v[82:83], v[82:83], v[94:95]
	v_pk_add_f32 v[80:81], v[80:81], v[92:93]
	v_mul_f32_e32 v84, 0xbfb8aa3b, v84
	v_mul_f32_e32 v80, 0xbfb8aa3b, v80
	v_mul_f32_e32 v85, 0xbfb8aa3b, v85
	v_mul_f32_e32 v81, 0xbfb8aa3b, v81
	v_mul_f32_e32 v86, 0xbfb8aa3b, v86
	v_mul_f32_e32 v82, 0xbfb8aa3b, v82
	v_mul_f32_e32 v87, 0xbfb8aa3b, v87
	v_mul_f32_e32 v83, 0xbfb8aa3b, v83
	v_exp_f32_e32 v84, v84
	v_exp_f32_e32 v80, v80
	v_exp_f32_e32 v85, v85
	v_exp_f32_e32 v81, v81
	v_exp_f32_e32 v86, v86
	v_exp_f32_e32 v82, v82
	v_exp_f32_e32 v87, v87
	v_exp_f32_e32 v83, v83
	v_add_f32_e32 v84, 1.0, v84
	v_add_f32_e32 v88, 1.0, v80
	v_add_f32_e32 v85, 1.0, v85
	v_add_f32_e32 v89, 1.0, v81
	v_add_f32_e32 v86, 1.0, v86
	v_add_f32_e32 v90, 1.0, v82
	v_add_f32_e32 v87, 1.0, v87
	v_add_f32_e32 v91, 1.0, v83
	v_rcp_f32_e32 v80, v84
	v_rcp_f32_e32 v88, v88
	v_rcp_f32_e32 v81, v85
	v_rcp_f32_e32 v82, v86
	v_rcp_f32_e32 v83, v87
	v_rcp_f32_e32 v90, v90
	v_rcp_f32_e32 v91, v91
	v_rcp_f32_e32 v89, v89
	v_pk_mul_f32 v[86:87], v[142:143], v[82:83] op_sel_hi:[0,1]
	v_pk_mul_f32 v[84:85], v[142:143], v[80:81] op_sel_hi:[0,1]
	v_pk_mul_f32 v[82:83], v[142:143], v[90:91] op_sel_hi:[0,1]
	v_pk_mul_f32 v[80:81], v[142:143], v[88:89] op_sel_hi:[0,1]

.LBB0_481:
	v_or_b32_e32 v80, 48, v146
	v_ashrrev_i32_e32 v81, 31, v80
	v_lshlrev_b64 v[80:81], 11, v[80:81]
	v_lshl_add_u64 v[80:81], v[148:149], 0, v[80:81]
	s_and_b64 vcc, exec, s[4:5]
	v_cvt_pk_bf16_f32 v76, v76, v77
	v_cvt_pk_bf16_f32 v77, v78, v79
	v_cvt_pk_bf16_f32 v78, v72, v73
	v_cvt_pk_bf16_f32 v79, v74, v75
	global_store_dwordx4 v[80:81], v[76:79], off nt
	s_cbranch_vccnz .LBB0_483
	global_load_dwordx4 v[72:75], v[144:145], off offset:512
	global_load_dwordx4 v[76:79], v[144:145], off offset:528
	s_waitcnt vmcnt(0)
	v_pk_add_f32 v[70:71], v[70:71], v[74:75]
	v_pk_add_f32 v[68:69], v[68:69], v[72:73]
	v_pk_add_f32 v[66:67], v[66:67], v[78:79]
	v_pk_add_f32 v[64:65], v[64:65], v[76:77]
	v_mul_f32_e32 v68, 0xbfb8aa3b, v68
	v_mul_f32_e32 v64, 0xbfb8aa3b, v64
	v_mul_f32_e32 v69, 0xbfb8aa3b, v69
	v_mul_f32_e32 v65, 0xbfb8aa3b, v65
	v_mul_f32_e32 v70, 0xbfb8aa3b, v70
	v_mul_f32_e32 v66, 0xbfb8aa3b, v66
	v_mul_f32_e32 v71, 0xbfb8aa3b, v71
	v_mul_f32_e32 v67, 0xbfb8aa3b, v67
	v_exp_f32_e32 v68, v68
	v_exp_f32_e32 v64, v64
	v_exp_f32_e32 v69, v69
	v_exp_f32_e32 v65, v65
	v_exp_f32_e32 v70, v70
	v_exp_f32_e32 v66, v66
	v_exp_f32_e32 v71, v71
	v_exp_f32_e32 v67, v67
	v_add_f32_e32 v68, 1.0, v68
	v_add_f32_e32 v72, 1.0, v64
	v_add_f32_e32 v69, 1.0, v69
	v_add_f32_e32 v73, 1.0, v65
	v_add_f32_e32 v70, 1.0, v70
	v_add_f32_e32 v74, 1.0, v66
	v_add_f32_e32 v71, 1.0, v71
	v_add_f32_e32 v75, 1.0, v67
	v_rcp_f32_e32 v64, v68
	v_rcp_f32_e32 v72, v72
	v_rcp_f32_e32 v65, v69
	v_rcp_f32_e32 v66, v70
	v_rcp_f32_e32 v67, v71
	v_rcp_f32_e32 v74, v74
	v_rcp_f32_e32 v75, v75
	v_rcp_f32_e32 v73, v73
	v_pk_mul_f32 v[70:71], v[142:143], v[66:67] op_sel_hi:[0,1]
	v_pk_mul_f32 v[68:69], v[142:143], v[64:65] op_sel_hi:[0,1]
	v_pk_mul_f32 v[66:67], v[142:143], v[74:75] op_sel_hi:[0,1]
	v_pk_mul_f32 v[64:65], v[142:143], v[72:73] op_sel_hi:[0,1]

.LBB0_981:
	v_ashrrev_i32_e32 v153, 31, v152
	v_lshlrev_b64 v[154:155], 6, v[152:153]
	v_lshl_add_u64 v[170:171], s[74:75], 0, v[154:155]
	s_waitcnt lgkmcnt(0)
	global_load_dwordx4 v[154:157], v[170:171], off
	global_load_dwordx4 v[162:165], v[170:171], off offset:16
	global_load_dwordx4 v[166:169], v[170:171], off offset:32
	s_nop 0
	global_load_dwordx4 v[170:173], v[170:171], off offset:48
	v_mov_b32_e32 v174, v124
	v_mov_b32_e32 v175, v116
	v_mov_b32_e32 v116, v125
	v_mov_b32_e32 v124, v126
	v_mov_b32_e32 v125, v118
	v_mov_b32_e32 v118, v127
	v_mov_b32_e32 v126, v120
	v_mov_b32_e32 v127, v112
	v_mov_b32_e32 v112, v121
	v_mov_b32_e32 v176, v122
	v_mov_b32_e32 v177, v114
	v_mov_b32_e32 v114, v123
	s_lshl_b32 s26, s26, 7
	v_mov_b64_e32 v[120:121], s[72:73]
	s_ashr_i32 s27, s26, 31
	v_mad_i64_i32 v[122:123], s[28:29], v152, s53, v[120:121]
	s_lshl_b64 s[26:27], s[26:27], 1
	v_lshl_add_u64 v[122:123], v[122:123], 0, s[26:27]
	v_lshl_add_u64 v[122:123], v[122:123], 0, s[8:9]
	s_waitcnt vmcnt(2)
	v_pk_add_f32 v[154:155], v[154:155], v[156:157]
	v_pk_add_f32 v[162:163], v[162:163], v[164:165]
	s_waitcnt vmcnt(0)
	v_pk_add_f32 v[166:167], v[166:167], v[168:169]
	v_pk_add_f32 v[170:171], v[170:171], v[172:173]
	v_pk_add_f32 v[154:155], v[154:155], v[162:163]
	v_pk_add_f32 v[166:167], v[166:167], v[170:171]
	v_mul_f32_e32 v116, v116, v117
	v_mul_f32_e32 v124, v124, v125
	v_mul_f32_e32 v118, v118, v119
	v_mul_f32_e32 v126, v126, v127
	v_pk_add_f32 v[154:155], v[154:155], v[166:167]
	v_mul_f32_e32 v174, v174, v175
	v_mul_f32_e32 v112, v112, v113
	v_mul_f32_e32 v176, v176, v177
	v_mul_f32_e32 v114, v114, v115
	v_add_f32_e32 v154, v154, v155
	v_fmamk_f32 v154, v154, 0x3a800000, v160
	v_rsq_f32_e32 v155, v154
	s_nop 0
	v_mul_f32_e32 v155, 0xbfb8aa3b, v155
	v_mul_f32_e32 v117, v155, v117
	v_mul_f32_e32 v125, v155, v125
	v_mul_f32_e32 v119, v155, v119
	v_mul_f32_e32 v127, v155, v127
	v_mul_f32_e32 v175, v155, v175
	v_mul_f32_e32 v113, v155, v113
	v_mul_f32_e32 v177, v155, v177
	v_mul_f32_e32 v115, v155, v115
	v_exp_f32_e32 v117, v117
	v_exp_f32_e32 v125, v125
	v_exp_f32_e32 v119, v119
	v_exp_f32_e32 v127, v127
	v_exp_f32_e32 v175, v175
	v_exp_f32_e32 v113, v113
	v_exp_f32_e32 v177, v177
	v_exp_f32_e32 v115, v115
	v_fma_f32 v117, v117, v154, v154
	v_fma_f32 v125, v125, v154, v154
	v_fma_f32 v119, v119, v154, v154
	v_fma_f32 v127, v127, v154, v154
	v_fma_f32 v175, v175, v154, v154
	v_fma_f32 v113, v113, v154, v154
	v_fma_f32 v177, v177, v154, v154
	v_fma_f32 v115, v115, v154, v154
	v_rcp_f32_e32 v117, v117
	v_rcp_f32_e32 v125, v125
	v_rcp_f32_e32 v119, v119
	v_rcp_f32_e32 v127, v127
	v_rcp_f32_e32 v175, v175
	v_rcp_f32_e32 v113, v113
	v_rcp_f32_e32 v177, v177
	v_rcp_f32_e32 v115, v115
	v_mul_f32_e32 v116, v116, v117
	v_mul_f32_e32 v124, v124, v125
	v_mul_f32_e32 v118, v118, v119
	v_mul_f32_e32 v126, v126, v127
	v_mul_f32_e32 v174, v174, v175
	v_mul_f32_e32 v112, v112, v113
	v_mul_f32_e32 v176, v176, v177
	v_mul_f32_e32 v114, v114, v115
	v_cvt_pk_bf16_f32 v113, v124, v118
	v_cvt_pk_bf16_f32 v115, v176, v114
	v_cvt_pk_bf16_f32 v114, v126, v112
	v_cvt_pk_bf16_f32 v112, v174, v116
	v_or_b32_e32 v126, 16, v152
	v_lshl_add_u64 v[116:117], v[122:123], 0, v[136:137]
	v_ashrrev_i32_e32 v127, 31, v126
	global_store_dwordx4 v[116:117], v[112:115], off nt
	v_mov_b32_e32 v162, v108
	v_mov_b32_e32 v163, v100
	v_lshlrev_b64 v[112:113], 6, v[126:127]
	v_lshl_add_u64 v[154:155], s[74:75], 0, v[112:113]
	global_load_dwordx4 v[112:115], v[154:155], off
	global_load_dwordx4 v[116:119], v[154:155], off offset:16
	global_load_dwordx4 v[122:125], v[154:155], off offset:32
	s_nop 0
	global_load_dwordx4 v[154:157], v[154:155], off offset:48
	v_mov_b32_e32 v100, v109
	v_mov_b32_e32 v108, v110
	v_mov_b32_e32 v109, v102
	v_mov_b32_e32 v102, v111
	v_mov_b32_e32 v110, v104
	v_mov_b32_e32 v111, v96
	v_mov_b32_e32 v96, v105
	v_mov_b32_e32 v104, v106
	v_mov_b32_e32 v105, v98
	v_mov_b32_e32 v98, v107
	s_waitcnt vmcnt(2)
	v_pk_add_f32 v[112:113], v[112:113], v[114:115]
	v_pk_add_f32 v[116:117], v[116:117], v[118:119]
	s_waitcnt vmcnt(0)
	v_pk_add_f32 v[122:123], v[122:123], v[124:125]
	v_pk_add_f32 v[154:155], v[154:155], v[156:157]
	v_pk_add_f32 v[112:113], v[112:113], v[116:117]
	v_pk_add_f32 v[122:123], v[122:123], v[154:155]
	v_mul_f32_e32 v100, v100, v101
	v_mul_f32_e32 v108, v108, v109
	v_mul_f32_e32 v162, v162, v163
	v_mul_f32_e32 v102, v102, v103
	v_pk_add_f32 v[112:113], v[112:113], v[122:123]
	v_mul_f32_e32 v110, v110, v111
	v_mul_f32_e32 v96, v96, v97
	v_mul_f32_e32 v104, v104, v105
	v_mul_f32_e32 v98, v98, v99
	v_add_f32_e32 v112, v112, v113
	v_fmamk_f32 v112, v112, 0x3a800000, v160
	v_rsq_f32_e32 v113, v112
	s_nop 0
	v_mul_f32_e32 v113, 0xbfb8aa3b, v113
	v_mul_f32_e32 v101, v113, v101
	v_mul_f32_e32 v109, v113, v109
	v_mul_f32_e32 v163, v113, v163
	v_mul_f32_e32 v103, v113, v103
	v_mul_f32_e32 v111, v113, v111
	v_mul_f32_e32 v97, v113, v97
	v_mul_f32_e32 v105, v113, v105
	v_mul_f32_e32 v99, v113, v99
	v_exp_f32_e32 v101, v101
	v_exp_f32_e32 v109, v109
	v_exp_f32_e32 v163, v163
	v_exp_f32_e32 v103, v103
	v_exp_f32_e32 v111, v111
	v_exp_f32_e32 v97, v97
	v_exp_f32_e32 v105, v105
	v_exp_f32_e32 v99, v99
	v_fma_f32 v101, v101, v112, v112
	v_fma_f32 v109, v109, v112, v112
	v_fma_f32 v163, v163, v112, v112
	v_fma_f32 v103, v103, v112, v112
	v_fma_f32 v111, v111, v112, v112
	v_fma_f32 v97, v97, v112, v112
	v_fma_f32 v105, v105, v112, v112
	v_fma_f32 v99, v99, v112, v112
	v_rcp_f32_e32 v101, v101
	v_rcp_f32_e32 v109, v109
	v_rcp_f32_e32 v163, v163
	v_rcp_f32_e32 v103, v103
	v_rcp_f32_e32 v111, v111
	v_rcp_f32_e32 v97, v97
	v_rcp_f32_e32 v105, v105
	v_rcp_f32_e32 v99, v99
	v_mul_f32_e32 v100, v100, v101
	v_mul_f32_e32 v108, v108, v109
	v_mul_f32_e32 v162, v162, v163
	v_mul_f32_e32 v102, v102, v103
	v_mul_f32_e32 v110, v110, v111
	v_mul_f32_e32 v96, v96, v97
	v_mul_f32_e32 v104, v104, v105
	v_mul_f32_e32 v98, v98, v99
	v_cvt_pk_bf16_f32 v97, v108, v102
	v_cvt_pk_bf16_f32 v99, v104, v98
	v_cvt_pk_bf16_f32 v98, v110, v96
	v_cvt_pk_bf16_f32 v96, v162, v100
	v_mad_i64_i32 v[112:113], s[28:29], v126, s53, v[120:121]
	v_lshl_add_u64 v[112:113], v[112:113], 0, s[26:27]
	v_lshl_add_u64 v[100:101], v[112:113], 0, s[8:9]
	v_or_b32_e32 v112, 32, v152
	v_lshl_add_u64 v[100:101], v[100:101], 0, v[136:137]
	v_ashrrev_i32_e32 v113, 31, v112
	global_store_dwordx4 v[100:101], v[96:99], off nt
	v_mov_b32_e32 v114, v92
	v_mov_b32_e32 v92, v94
	v_lshlrev_b64 v[96:97], 6, v[112:113]
	v_lshl_add_u64 v[108:109], s[74:75], 0, v[96:97]
	global_load_dwordx4 v[96:99], v[108:109], off
	global_load_dwordx4 v[100:103], v[108:109], off offset:16
	global_load_dwordx4 v[104:107], v[108:109], off offset:32
	s_nop 0
	global_load_dwordx4 v[108:111], v[108:109], off offset:48
	v_mov_b32_e32 v94, v80
	v_mov_b32_e32 v80, v82
	v_mov_b32_e32 v115, v88
	v_mov_b32_e32 v88, v93
	v_mov_b32_e32 v93, v90
	v_mov_b32_e32 v90, v95
	v_mov_b32_e32 v95, v84
	v_mov_b32_e32 v84, v81
	v_mov_b32_e32 v81, v86
	v_mov_b32_e32 v86, v83
	s_waitcnt vmcnt(2)
	v_pk_add_f32 v[96:97], v[96:97], v[98:99]
	v_pk_add_f32 v[100:101], v[100:101], v[102:103]
	s_waitcnt vmcnt(0)
	v_pk_add_f32 v[104:105], v[104:105], v[106:107]
	v_pk_add_f32 v[108:109], v[108:109], v[110:111]
	v_pk_add_f32 v[96:97], v[96:97], v[100:101]
	v_pk_add_f32 v[104:105], v[104:105], v[108:109]
	v_mul_f32_e32 v114, v114, v115
	v_mul_f32_e32 v88, v88, v89
	v_mul_f32_e32 v92, v92, v93
	v_mul_f32_e32 v90, v90, v91
	v_pk_add_f32 v[96:97], v[96:97], v[104:105]
	v_mul_f32_e32 v94, v94, v95
	v_mul_f32_e32 v84, v84, v85
	v_mul_f32_e32 v80, v80, v81
	v_mul_f32_e32 v86, v86, v87
	v_add_f32_e32 v96, v96, v97
	v_fmamk_f32 v96, v96, 0x3a800000, v160
	v_rsq_f32_e32 v97, v96
	s_nop 0
	v_mul_f32_e32 v97, 0xbfb8aa3b, v97
	v_mul_f32_e32 v115, v97, v115
	v_mul_f32_e32 v89, v97, v89
	v_mul_f32_e32 v93, v97, v93
	v_mul_f32_e32 v91, v97, v91
	v_mul_f32_e32 v95, v97, v95
	v_mul_f32_e32 v85, v97, v85
	v_mul_f32_e32 v81, v97, v81
	v_mul_f32_e32 v87, v97, v87
	v_exp_f32_e32 v115, v115
	v_exp_f32_e32 v89, v89
	v_exp_f32_e32 v93, v93
	v_exp_f32_e32 v91, v91
	v_exp_f32_e32 v95, v95
	v_exp_f32_e32 v85, v85
	v_exp_f32_e32 v81, v81
	v_exp_f32_e32 v87, v87
	v_fma_f32 v115, v115, v96, v96
	v_fma_f32 v89, v89, v96, v96
	v_fma_f32 v93, v93, v96, v96
	v_fma_f32 v91, v91, v96, v96
	v_fma_f32 v95, v95, v96, v96
	v_fma_f32 v85, v85, v96, v96
	v_fma_f32 v81, v81, v96, v96
	v_fma_f32 v87, v87, v96, v96
	v_rcp_f32_e32 v115, v115
	v_rcp_f32_e32 v89, v89
	v_rcp_f32_e32 v93, v93
	v_rcp_f32_e32 v91, v91
	v_rcp_f32_e32 v95, v95
	v_rcp_f32_e32 v85, v85
	v_rcp_f32_e32 v81, v81
	v_rcp_f32_e32 v87, v87
	v_mul_f32_e32 v114, v114, v115
	v_mul_f32_e32 v88, v88, v89
	v_mul_f32_e32 v92, v92, v93
	v_mul_f32_e32 v90, v90, v91
	v_mul_f32_e32 v94, v94, v95
	v_mul_f32_e32 v84, v84, v85
	v_mul_f32_e32 v80, v80, v81
	v_mul_f32_e32 v86, v86, v87
	v_cvt_pk_bf16_f32 v81, v92, v90
	v_cvt_pk_bf16_f32 v82, v94, v84
	v_cvt_pk_bf16_f32 v83, v80, v86
	v_cvt_pk_bf16_f32 v80, v114, v88
	v_mad_i64_i32 v[96:97], s[28:29], v112, s53, v[120:121]
	v_lshl_add_u64 v[84:85], v[96:97], 0, s[26:27]
	v_lshl_add_u64 v[84:85], v[84:85], 0, s[8:9]
	v_or_b32_e32 v96, 48, v152
	v_lshl_add_u64 v[84:85], v[84:85], 0, v[136:137]
	v_ashrrev_i32_e32 v97, 31, v96
	global_store_dwordx4 v[84:85], v[80:83], off nt
	v_mov_b32_e32 v98, v76
	v_mov_b32_e32 v99, v72
	v_lshlrev_b64 v[80:81], 6, v[96:97]
	v_lshl_add_u64 v[92:93], s[74:75], 0, v[80:81]
	global_load_dwordx4 v[80:83], v[92:93], off
	global_load_dwordx4 v[84:87], v[92:93], off offset:16
	global_load_dwordx4 v[88:91], v[92:93], off offset:32
	s_nop 0
	global_load_dwordx4 v[92:95], v[92:93], off offset:48
	v_mov_b32_e32 v72, v77
	v_mov_b32_e32 v76, v78
	v_mov_b32_e32 v77, v74
	v_mov_b32_e32 v74, v79
	v_mov_b32_e32 v78, v64
	v_mov_b32_e32 v79, v68
	v_mov_b32_e32 v68, v65
	s_waitcnt vmcnt(2)
	v_pk_add_f32 v[80:81], v[80:81], v[82:83]
	v_pk_add_f32 v[84:85], v[84:85], v[86:87]
	s_waitcnt vmcnt(0)
	v_pk_add_f32 v[88:89], v[88:89], v[90:91]
	v_pk_add_f32 v[92:93], v[92:93], v[94:95]
	v_pk_add_f32 v[80:81], v[80:81], v[84:85]
	v_pk_add_f32 v[88:89], v[88:89], v[92:93]
	v_mul_f32_e32 v98, v98, v99
	v_mul_f32_e32 v72, v72, v73
	v_mul_f32_e32 v76, v76, v77
	v_mul_f32_e32 v68, v68, v69
	v_pk_add_f32 v[80:81], v[80:81], v[88:89]
	v_mul_f32_e32 v66, v66, v70
	v_mul_f32_e32 v74, v74, v75
	v_mul_f32_e32 v78, v78, v79
	v_mul_f32_e32 v67, v67, v71
	v_add_f32_e32 v80, v80, v81
	v_fmamk_f32 v80, v80, 0x3a800000, v160
	v_rsq_f32_e32 v81, v80
	s_nop 0
	v_mul_f32_e32 v81, 0xbfb8aa3b, v81
	v_mul_f32_e32 v99, v81, v99
	v_mul_f32_e32 v73, v81, v73
	v_mul_f32_e32 v77, v81, v77
	v_mul_f32_e32 v69, v81, v69
	v_mul_f32_e32 v70, v81, v70
	v_mul_f32_e32 v75, v81, v75
	v_mul_f32_e32 v79, v81, v79
	v_mul_f32_e32 v71, v81, v71
	v_exp_f32_e32 v99, v99
	v_exp_f32_e32 v73, v73
	v_exp_f32_e32 v77, v77
	v_exp_f32_e32 v69, v69
	v_exp_f32_e32 v70, v70
	v_exp_f32_e32 v75, v75
	v_exp_f32_e32 v79, v79
	v_exp_f32_e32 v71, v71
	v_fma_f32 v99, v99, v80, v80
	v_fma_f32 v73, v73, v80, v80
	v_fma_f32 v77, v77, v80, v80
	v_fma_f32 v69, v69, v80, v80
	v_fma_f32 v70, v70, v80, v80
	v_fma_f32 v75, v75, v80, v80
	v_fma_f32 v79, v79, v80, v80
	v_fma_f32 v71, v71, v80, v80
	v_rcp_f32_e32 v99, v99
	v_rcp_f32_e32 v73, v73
	v_rcp_f32_e32 v77, v77
	v_rcp_f32_e32 v69, v69
	v_rcp_f32_e32 v70, v70
	v_rcp_f32_e32 v75, v75
	v_rcp_f32_e32 v79, v79
	v_rcp_f32_e32 v71, v71
	v_mul_f32_e32 v98, v98, v99
	v_mul_f32_e32 v72, v72, v73
	v_mul_f32_e32 v76, v76, v77
	v_mul_f32_e32 v68, v68, v69
	v_mul_f32_e32 v66, v66, v70
	v_mul_f32_e32 v74, v74, v75
	v_mul_f32_e32 v78, v78, v79
	v_mul_f32_e32 v67, v67, v71
	v_cvt_pk_bf16_f32 v64, v98, v72
	v_cvt_pk_bf16_f32 v65, v76, v74
	v_cvt_pk_bf16_f32 v67, v66, v67
	v_cvt_pk_bf16_f32 v66, v78, v68
	v_mad_i64_i32 v[68:69], s[28:29], v96, s53, v[120:121]
	v_lshl_add_u64 v[68:69], v[68:69], 0, s[26:27]
	v_lshl_add_u64 v[68:69], v[68:69], 0, s[8:9]
	v_add_u32_e32 v80, 0x80, v152
	v_lshl_add_u64 v[68:69], v[68:69], 0, v[136:137]
	v_ashrrev_i32_e32 v81, 31, v80
	global_store_dwordx4 v[68:69], v[64:67], off nt
	v_mov_b32_e32 v82, v60
	v_mov_b32_e32 v83, v56
	v_lshlrev_b64 v[64:65], 6, v[80:81]
	v_lshl_add_u64 v[76:77], s[74:75], 0, v[64:65]
	global_load_dwordx4 v[64:67], v[76:77], off
	global_load_dwordx4 v[68:71], v[76:77], off offset:16
	global_load_dwordx4 v[72:75], v[76:77], off offset:32
	s_nop 0
	global_load_dwordx4 v[76:79], v[76:77], off offset:48
	v_mov_b32_e32 v56, v61
	v_mov_b32_e32 v60, v62
	v_mov_b32_e32 v61, v58
	v_mov_b32_e32 v58, v63
	v_mov_b32_e32 v62, v48
	v_mov_b32_e32 v63, v52
	v_mov_b32_e32 v52, v49
	s_waitcnt vmcnt(2)
	v_pk_add_f32 v[64:65], v[64:65], v[66:67]
	v_pk_add_f32 v[68:69], v[68:69], v[70:71]
	s_waitcnt vmcnt(0)
	v_pk_add_f32 v[72:73], v[72:73], v[74:75]
	v_pk_add_f32 v[76:77], v[76:77], v[78:79]
	v_pk_add_f32 v[64:65], v[64:65], v[68:69]
	v_pk_add_f32 v[72:73], v[72:73], v[76:77]
	v_mul_f32_e32 v82, v82, v83
	v_mul_f32_e32 v56, v56, v57
	v_mul_f32_e32 v60, v60, v61
	v_mul_f32_e32 v52, v52, v53
	v_pk_add_f32 v[64:65], v[64:65], v[72:73]
	v_mul_f32_e32 v50, v50, v54
	v_mul_f32_e32 v58, v58, v59
	v_mul_f32_e32 v62, v62, v63
	v_mul_f32_e32 v51, v51, v55
	v_add_f32_e32 v64, v64, v65
	v_fmamk_f32 v64, v64, 0x3a800000, v160
	v_rsq_f32_e32 v65, v64
	s_nop 0
	v_mul_f32_e32 v65, 0xbfb8aa3b, v65
	v_mul_f32_e32 v83, v65, v83
	v_mul_f32_e32 v57, v65, v57
	v_mul_f32_e32 v61, v65, v61
	v_mul_f32_e32 v53, v65, v53
	v_mul_f32_e32 v54, v65, v54
	v_mul_f32_e32 v59, v65, v59
	v_mul_f32_e32 v63, v65, v63
	v_mul_f32_e32 v55, v65, v55
	v_exp_f32_e32 v83, v83
	v_exp_f32_e32 v57, v57
	v_exp_f32_e32 v61, v61
	v_exp_f32_e32 v53, v53
	v_exp_f32_e32 v54, v54
	v_exp_f32_e32 v59, v59
	v_exp_f32_e32 v63, v63
	v_exp_f32_e32 v55, v55
	v_fma_f32 v83, v83, v64, v64
	v_fma_f32 v57, v57, v64, v64
	v_fma_f32 v61, v61, v64, v64
	v_fma_f32 v53, v53, v64, v64
	v_fma_f32 v54, v54, v64, v64
	v_fma_f32 v59, v59, v64, v64
	v_fma_f32 v63, v63, v64, v64
	v_fma_f32 v55, v55, v64, v64
	v_rcp_f32_e32 v83, v83
	v_rcp_f32_e32 v57, v57
	v_rcp_f32_e32 v61, v61
	v_rcp_f32_e32 v53, v53
	v_rcp_f32_e32 v54, v54
	v_rcp_f32_e32 v59, v59
	v_rcp_f32_e32 v63, v63
	v_rcp_f32_e32 v55, v55
	v_mul_f32_e32 v82, v82, v83
	v_mul_f32_e32 v56, v56, v57
	v_mul_f32_e32 v60, v60, v61
	v_mul_f32_e32 v52, v52, v53
	v_mul_f32_e32 v50, v50, v54
	v_mul_f32_e32 v58, v58, v59
	v_mul_f32_e32 v62, v62, v63
	v_mul_f32_e32 v51, v51, v55
	v_cvt_pk_bf16_f32 v48, v82, v56
	v_cvt_pk_bf16_f32 v49, v60, v58
	v_cvt_pk_bf16_f32 v51, v50, v51
	v_cvt_pk_bf16_f32 v50, v62, v52
	v_mad_i64_i32 v[52:53], s[28:29], v80, s53, v[120:121]
	v_lshl_add_u64 v[52:53], v[52:53], 0, s[26:27]
	v_lshl_add_u64 v[52:53], v[52:53], 0, s[8:9]
	v_add_u32_e32 v64, 0x90, v152
	v_lshl_add_u64 v[52:53], v[52:53], 0, v[136:137]
	v_ashrrev_i32_e32 v65, 31, v64
	global_store_dwordx4 v[52:53], v[48:51], off nt
	v_mov_b32_e32 v66, v44
	v_mov_b32_e32 v67, v40
	v_lshlrev_b64 v[48:49], 6, v[64:65]
	v_lshl_add_u64 v[60:61], s[74:75], 0, v[48:49]
	global_load_dwordx4 v[48:51], v[60:61], off
	global_load_dwordx4 v[52:55], v[60:61], off offset:16
	global_load_dwordx4 v[56:59], v[60:61], off offset:32
	s_nop 0
	global_load_dwordx4 v[60:63], v[60:61], off offset:48
	v_mov_b32_e32 v40, v45
	v_mov_b32_e32 v44, v46
	v_mov_b32_e32 v45, v42
	v_mov_b32_e32 v42, v47
	v_mov_b32_e32 v46, v32
	v_mov_b32_e32 v47, v36
	v_mov_b32_e32 v36, v33
	s_waitcnt vmcnt(2)
	v_pk_add_f32 v[48:49], v[48:49], v[50:51]
	v_pk_add_f32 v[52:53], v[52:53], v[54:55]
	s_waitcnt vmcnt(0)
	v_pk_add_f32 v[56:57], v[56:57], v[58:59]
	v_pk_add_f32 v[60:61], v[60:61], v[62:63]
	v_pk_add_f32 v[48:49], v[48:49], v[52:53]
	v_pk_add_f32 v[56:57], v[56:57], v[60:61]
	v_mul_f32_e32 v66, v66, v67
	v_mul_f32_e32 v40, v40, v41
	v_mul_f32_e32 v44, v44, v45
	v_mul_f32_e32 v36, v36, v37
	v_pk_add_f32 v[48:49], v[48:49], v[56:57]
	v_mul_f32_e32 v34, v34, v38
	v_mul_f32_e32 v42, v42, v43
	v_mul_f32_e32 v46, v46, v47
	v_mul_f32_e32 v35, v35, v39
	v_add_f32_e32 v48, v48, v49
	v_fmamk_f32 v48, v48, 0x3a800000, v160
	v_rsq_f32_e32 v49, v48
	s_nop 0
	v_mul_f32_e32 v49, 0xbfb8aa3b, v49
	v_mul_f32_e32 v67, v49, v67
	v_mul_f32_e32 v41, v49, v41
	v_mul_f32_e32 v45, v49, v45
	v_mul_f32_e32 v37, v49, v37
	v_mul_f32_e32 v38, v49, v38
	v_mul_f32_e32 v43, v49, v43
	v_mul_f32_e32 v47, v49, v47
	v_mul_f32_e32 v39, v49, v39
	v_exp_f32_e32 v67, v67
	v_exp_f32_e32 v41, v41
	v_exp_f32_e32 v45, v45
	v_exp_f32_e32 v37, v37
	v_exp_f32_e32 v38, v38
	v_exp_f32_e32 v43, v43
	v_exp_f32_e32 v47, v47
	v_exp_f32_e32 v39, v39
	v_fma_f32 v67, v67, v48, v48
	v_fma_f32 v41, v41, v48, v48
	v_fma_f32 v45, v45, v48, v48
	v_fma_f32 v37, v37, v48, v48
	v_fma_f32 v38, v38, v48, v48
	v_fma_f32 v43, v43, v48, v48
	v_fma_f32 v47, v47, v48, v48
	v_fma_f32 v39, v39, v48, v48
	v_rcp_f32_e32 v67, v67
	v_rcp_f32_e32 v41, v41
	v_rcp_f32_e32 v45, v45
	v_rcp_f32_e32 v37, v37
	v_rcp_f32_e32 v38, v38
	v_rcp_f32_e32 v43, v43
	v_rcp_f32_e32 v47, v47
	v_rcp_f32_e32 v39, v39
	v_mul_f32_e32 v66, v66, v67
	v_mul_f32_e32 v40, v40, v41
	v_mul_f32_e32 v44, v44, v45
	v_mul_f32_e32 v36, v36, v37
	v_mul_f32_e32 v34, v34, v38
	v_mul_f32_e32 v42, v42, v43
	v_mul_f32_e32 v46, v46, v47
	v_mul_f32_e32 v35, v35, v39
	v_cvt_pk_bf16_f32 v32, v66, v40
	v_cvt_pk_bf16_f32 v33, v44, v42
	v_cvt_pk_bf16_f32 v35, v34, v35
	v_cvt_pk_bf16_f32 v34, v46, v36
	v_mad_i64_i32 v[36:37], s[28:29], v64, s53, v[120:121]
	v_lshl_add_u64 v[36:37], v[36:37], 0, s[26:27]
	v_lshl_add_u64 v[36:37], v[36:37], 0, s[8:9]
	v_add_u32_e32 v48, 0xa0, v152
	v_lshl_add_u64 v[36:37], v[36:37], 0, v[136:137]
	v_ashrrev_i32_e32 v49, 31, v48
	global_store_dwordx4 v[36:37], v[32:35], off nt
	v_mov_b32_e32 v50, v28
	v_mov_b32_e32 v51, v24
	v_lshlrev_b64 v[32:33], 6, v[48:49]
	v_lshl_add_u64 v[44:45], s[74:75], 0, v[32:33]
	global_load_dwordx4 v[32:35], v[44:45], off
	global_load_dwordx4 v[36:39], v[44:45], off offset:16
	global_load_dwordx4 v[40:43], v[44:45], off offset:32
	s_nop 0
	global_load_dwordx4 v[44:47], v[44:45], off offset:48
	v_mov_b32_e32 v24, v29
	v_mov_b32_e32 v28, v30
	v_mov_b32_e32 v29, v26
	v_mov_b32_e32 v26, v31
	v_mov_b32_e32 v30, v16
	v_mov_b32_e32 v31, v20
	v_mov_b32_e32 v20, v17
	s_waitcnt vmcnt(2)
	v_pk_add_f32 v[32:33], v[32:33], v[34:35]
	v_pk_add_f32 v[36:37], v[36:37], v[38:39]
	s_waitcnt vmcnt(0)
	v_pk_add_f32 v[40:41], v[40:41], v[42:43]
	v_pk_add_f32 v[44:45], v[44:45], v[46:47]
	v_pk_add_f32 v[32:33], v[32:33], v[36:37]
	v_pk_add_f32 v[40:41], v[40:41], v[44:45]
	v_mul_f32_e32 v50, v50, v51
	v_mul_f32_e32 v24, v24, v25
	v_mul_f32_e32 v28, v28, v29
	v_mul_f32_e32 v20, v20, v21
	v_pk_add_f32 v[32:33], v[32:33], v[40:41]
	v_mul_f32_e32 v18, v18, v22
	v_mul_f32_e32 v26, v26, v27
	v_mul_f32_e32 v30, v30, v31
	v_mul_f32_e32 v19, v19, v23
	v_add_f32_e32 v32, v32, v33
	v_fmamk_f32 v32, v32, 0x3a800000, v160
	v_rsq_f32_e32 v33, v32
	s_nop 0
	v_mul_f32_e32 v33, 0xbfb8aa3b, v33
	v_mul_f32_e32 v51, v33, v51
	v_mul_f32_e32 v25, v33, v25
	v_mul_f32_e32 v29, v33, v29
	v_mul_f32_e32 v21, v33, v21
	v_mul_f32_e32 v22, v33, v22
	v_mul_f32_e32 v27, v33, v27
	v_mul_f32_e32 v31, v33, v31
	v_mul_f32_e32 v23, v33, v23
	v_exp_f32_e32 v51, v51
	v_exp_f32_e32 v25, v25
	v_exp_f32_e32 v29, v29
	v_exp_f32_e32 v21, v21
	v_exp_f32_e32 v22, v22
	v_exp_f32_e32 v27, v27
	v_exp_f32_e32 v31, v31
	v_exp_f32_e32 v23, v23
	v_fma_f32 v51, v51, v32, v32
	v_fma_f32 v25, v25, v32, v32
	v_fma_f32 v29, v29, v32, v32
	v_fma_f32 v21, v21, v32, v32
	v_fma_f32 v22, v22, v32, v32
	v_fma_f32 v27, v27, v32, v32
	v_fma_f32 v31, v31, v32, v32
	v_fma_f32 v23, v23, v32, v32
	v_rcp_f32_e32 v51, v51
	v_rcp_f32_e32 v25, v25
	v_rcp_f32_e32 v29, v29
	v_rcp_f32_e32 v21, v21
	v_rcp_f32_e32 v22, v22
	v_rcp_f32_e32 v27, v27
	v_rcp_f32_e32 v31, v31
	v_rcp_f32_e32 v23, v23
	v_mul_f32_e32 v50, v50, v51
	v_mul_f32_e32 v24, v24, v25
	v_mul_f32_e32 v28, v28, v29
	v_mul_f32_e32 v20, v20, v21
	v_mul_f32_e32 v18, v18, v22
	v_mul_f32_e32 v26, v26, v27
	v_mul_f32_e32 v30, v30, v31
	v_mul_f32_e32 v19, v19, v23
	v_cvt_pk_bf16_f32 v16, v50, v24
	v_cvt_pk_bf16_f32 v17, v28, v26
	v_cvt_pk_bf16_f32 v19, v18, v19
	v_cvt_pk_bf16_f32 v18, v30, v20
	v_mad_i64_i32 v[20:21], s[28:29], v48, s53, v[120:121]
	v_lshl_add_u64 v[20:21], v[20:21], 0, s[26:27]
	v_lshl_add_u64 v[20:21], v[20:21], 0, s[8:9]
	v_add_u32_e32 v32, 0xb0, v152
	v_lshl_add_u64 v[20:21], v[20:21], 0, v[136:137]
	v_ashrrev_i32_e32 v33, 31, v32
	global_store_dwordx4 v[20:21], v[16:19], off nt
	v_mov_b32_e32 v34, v12
	v_mov_b32_e32 v35, v8
	v_lshlrev_b64 v[16:17], 6, v[32:33]
	v_lshl_add_u64 v[28:29], s[74:75], 0, v[16:17]
	global_load_dwordx4 v[16:19], v[28:29], off
	global_load_dwordx4 v[20:23], v[28:29], off offset:16
	global_load_dwordx4 v[24:27], v[28:29], off offset:32
	s_nop 0
	global_load_dwordx4 v[28:31], v[28:29], off offset:48
	v_mov_b32_e32 v8, v13
	v_mov_b32_e32 v12, v14
	v_mov_b32_e32 v13, v10
	v_mov_b32_e32 v10, v15
	v_mov_b32_e32 v14, v0
	v_mov_b32_e32 v15, v4
	v_mov_b32_e32 v4, v1
	s_waitcnt vmcnt(2)
	v_pk_add_f32 v[16:17], v[16:17], v[18:19]
	v_pk_add_f32 v[20:21], v[20:21], v[22:23]
	s_waitcnt vmcnt(0)
	v_pk_add_f32 v[24:25], v[24:25], v[26:27]
	v_pk_add_f32 v[28:29], v[28:29], v[30:31]
	v_pk_add_f32 v[16:17], v[16:17], v[20:21]
	v_pk_add_f32 v[24:25], v[24:25], v[28:29]
	v_mul_f32_e32 v34, v34, v35
	v_mul_f32_e32 v8, v8, v9
	v_mul_f32_e32 v12, v12, v13
	v_mul_f32_e32 v4, v4, v5
	v_pk_add_f32 v[16:17], v[16:17], v[24:25]
	v_mul_f32_e32 v2, v2, v6
	v_mul_f32_e32 v10, v10, v11
	v_mul_f32_e32 v14, v14, v15
	v_mul_f32_e32 v3, v3, v7
	v_add_f32_e32 v16, v16, v17
	v_fmamk_f32 v16, v16, 0x3a800000, v160
	v_rsq_f32_e32 v17, v16
	s_nop 0
	v_mul_f32_e32 v17, 0xbfb8aa3b, v17
	v_mul_f32_e32 v35, v17, v35
	v_mul_f32_e32 v9, v17, v9
	v_mul_f32_e32 v13, v17, v13
	v_mul_f32_e32 v5, v17, v5
	v_mul_f32_e32 v6, v17, v6
	v_mul_f32_e32 v11, v17, v11
	v_mul_f32_e32 v15, v17, v15
	v_mul_f32_e32 v7, v17, v7
	v_exp_f32_e32 v35, v35
	v_exp_f32_e32 v9, v9
	v_exp_f32_e32 v13, v13
	v_exp_f32_e32 v5, v5
	v_exp_f32_e32 v6, v6
	v_exp_f32_e32 v11, v11
	v_exp_f32_e32 v15, v15
	v_exp_f32_e32 v7, v7
	v_fma_f32 v35, v35, v16, v16
	v_fma_f32 v9, v9, v16, v16
	v_fma_f32 v13, v13, v16, v16
	v_fma_f32 v5, v5, v16, v16
	v_fma_f32 v6, v6, v16, v16
	v_fma_f32 v11, v11, v16, v16
	v_fma_f32 v15, v15, v16, v16
	v_fma_f32 v7, v7, v16, v16
	v_rcp_f32_e32 v35, v35
	v_rcp_f32_e32 v9, v9
	v_rcp_f32_e32 v13, v13
	v_rcp_f32_e32 v5, v5
	v_rcp_f32_e32 v6, v6
	v_rcp_f32_e32 v11, v11
	v_rcp_f32_e32 v15, v15
	v_rcp_f32_e32 v7, v7
	v_mul_f32_e32 v34, v34, v35
	v_mul_f32_e32 v8, v8, v9
	v_mul_f32_e32 v12, v12, v13
	v_mul_f32_e32 v4, v4, v5
	v_mul_f32_e32 v2, v2, v6
	v_mul_f32_e32 v10, v10, v11
	v_mul_f32_e32 v14, v14, v15
	v_mul_f32_e32 v3, v3, v7
	v_cvt_pk_bf16_f32 v0, v34, v8
	v_cvt_pk_bf16_f32 v1, v12, v10
	v_cvt_pk_bf16_f32 v3, v2, v3
	v_cvt_pk_bf16_f32 v2, v14, v4
	v_mad_i64_i32 v[4:5], s[28:29], v32, s53, v[120:121]
	v_lshl_add_u64 v[4:5], v[4:5], 0, s[26:27]
	v_lshl_add_u64 v[4:5], v[4:5], 0, s[8:9]
	v_lshl_add_u64 v[4:5], v[4:5], 0, v[136:137]
	global_store_dwordx4 v[4:5], v[0:3], off nt
	s_andn2_b64 vcc, exec, s[4:5]
	s_mov_b64 s[4:5], -1
	s_cbranch_vccnz .LBB0_973
	s_branch .LBB0_1007

.LBB0_1135:
	v_ashrrev_i32_e32 v155, 31, v154
	v_lshlrev_b64 v[156:157], 6, v[154:155]
	v_lshl_add_u64 v[156:157], s[74:75], 0, v[156:157]
	global_load_dwordx4 v[166:169], v[156:157], off
	global_load_dwordx4 v[170:173], v[156:157], off offset:16
	global_load_dwordx4 v[174:177], v[156:157], off offset:32
	global_load_dwordx4 v[178:181], v[156:157], off offset:48
	v_mov_b32_e32 v156, v124
	v_mov_b32_e32 v157, v116
	v_mov_b32_e32 v116, v125
	v_mov_b32_e32 v124, v126
	v_mov_b32_e32 v125, v118
	v_mov_b32_e32 v118, v127
	v_mov_b32_e32 v126, v120
	v_mov_b32_e32 v127, v112
	v_mov_b32_e32 v112, v121
	v_mov_b32_e32 v182, v122
	v_mov_b32_e32 v183, v114
	v_mov_b32_e32 v114, v123
	s_lshl_b32 s28, s28, 7
	v_mov_b64_e32 v[120:121], s[72:73]
	s_ashr_i32 s29, s28, 31
	v_mad_i64_i32 v[122:123], s[30:31], v154, s54, v[120:121]
	s_lshl_b64 s[28:29], s[28:29], 1
	v_lshl_add_u64 v[122:123], v[122:123], 0, s[28:29]
	v_lshl_add_u64 v[122:123], v[122:123], 0, s[8:9]
	s_waitcnt vmcnt(2)
	v_pk_add_f32 v[166:167], v[166:167], v[168:169]
	v_pk_add_f32 v[170:171], v[170:171], v[172:173]
	s_waitcnt vmcnt(0)
	v_pk_add_f32 v[174:175], v[174:175], v[176:177]
	v_pk_add_f32 v[178:179], v[178:179], v[180:181]
	v_pk_add_f32 v[166:167], v[166:167], v[170:171]
	v_pk_add_f32 v[174:175], v[174:175], v[178:179]
	v_mul_f32_e32 v116, v116, v117
	v_mul_f32_e32 v124, v124, v125
	v_mul_f32_e32 v118, v118, v119
	v_mul_f32_e32 v126, v126, v127
	v_pk_add_f32 v[166:167], v[166:167], v[174:175]
	v_mul_f32_e32 v156, v156, v157
	v_mul_f32_e32 v112, v112, v113
	v_mul_f32_e32 v182, v182, v183
	v_mul_f32_e32 v114, v114, v115
	v_add_f32_e32 v166, v166, v167
	v_fmamk_f32 v166, v166, 0x3a800000, v163
	v_rsq_f32_e32 v167, v166
	s_nop 0
	v_mul_f32_e32 v167, 0xbfb8aa3b, v167
	v_mul_f32_e32 v117, v167, v117
	v_mul_f32_e32 v125, v167, v125
	v_mul_f32_e32 v119, v167, v119
	v_mul_f32_e32 v127, v167, v127
	v_mul_f32_e32 v157, v167, v157
	v_mul_f32_e32 v113, v167, v113
	v_mul_f32_e32 v183, v167, v183
	v_mul_f32_e32 v115, v167, v115
	v_exp_f32_e32 v117, v117
	v_exp_f32_e32 v125, v125
	v_exp_f32_e32 v119, v119
	v_exp_f32_e32 v127, v127
	v_exp_f32_e32 v157, v157
	v_exp_f32_e32 v113, v113
	v_exp_f32_e32 v183, v183
	v_exp_f32_e32 v115, v115
	v_fma_f32 v117, v117, v166, v166
	v_fma_f32 v125, v125, v166, v166
	v_fma_f32 v119, v119, v166, v166
	v_fma_f32 v127, v127, v166, v166
	v_fma_f32 v157, v157, v166, v166
	v_fma_f32 v113, v113, v166, v166
	v_fma_f32 v183, v183, v166, v166
	v_fma_f32 v115, v115, v166, v166
	v_rcp_f32_e32 v117, v117
	v_rcp_f32_e32 v125, v125
	v_rcp_f32_e32 v119, v119
	v_rcp_f32_e32 v127, v127
	v_rcp_f32_e32 v157, v157
	v_rcp_f32_e32 v113, v113
	v_rcp_f32_e32 v183, v183
	v_rcp_f32_e32 v115, v115
	v_mul_f32_e32 v116, v116, v117
	v_mul_f32_e32 v124, v124, v125
	v_mul_f32_e32 v118, v118, v119
	v_mul_f32_e32 v126, v126, v127
	v_mul_f32_e32 v156, v156, v157
	v_mul_f32_e32 v112, v112, v113
	v_mul_f32_e32 v182, v182, v183
	v_mul_f32_e32 v114, v114, v115
	v_cvt_pk_bf16_f32 v113, v124, v118
	v_cvt_pk_bf16_f32 v115, v182, v114
	v_cvt_pk_bf16_f32 v114, v126, v112
	v_cvt_pk_bf16_f32 v112, v156, v116
	v_or_b32_e32 v126, 16, v154
	v_lshl_add_u64 v[116:117], v[122:123], 0, v[136:137]
	v_ashrrev_i32_e32 v127, 31, v126
	global_store_dwordx4 v[116:117], v[112:115], off nt
	s_nop 1
	v_lshlrev_b64 v[112:113], 6, v[126:127]
	v_lshl_add_u64 v[156:157], s[74:75], 0, v[112:113]
	global_load_dwordx4 v[112:115], v[156:157], off
	global_load_dwordx4 v[116:119], v[156:157], off offset:16
	global_load_dwordx4 v[122:125], v[156:157], off offset:32
	global_load_dwordx4 v[166:169], v[156:157], off offset:48
	v_mov_b32_e32 v156, v108
	v_mov_b32_e32 v157, v100
	v_mov_b32_e32 v100, v109
	v_mov_b32_e32 v108, v110
	v_mov_b32_e32 v109, v102
	v_mov_b32_e32 v102, v111
	v_mov_b32_e32 v110, v104
	v_mov_b32_e32 v111, v96
	v_mov_b32_e32 v96, v105
	v_mov_b32_e32 v104, v106
	v_mov_b32_e32 v105, v98
	v_mov_b32_e32 v98, v107
	s_waitcnt vmcnt(2)
	v_pk_add_f32 v[112:113], v[112:113], v[114:115]
	v_pk_add_f32 v[116:117], v[116:117], v[118:119]
	s_waitcnt vmcnt(0)
	v_pk_add_f32 v[122:123], v[122:123], v[124:125]
	v_pk_add_f32 v[166:167], v[166:167], v[168:169]
	v_pk_add_f32 v[112:113], v[112:113], v[116:117]
	v_pk_add_f32 v[122:123], v[122:123], v[166:167]
	v_mul_f32_e32 v100, v100, v101
	v_mul_f32_e32 v108, v108, v109
	v_mul_f32_e32 v156, v156, v157
	v_mul_f32_e32 v102, v102, v103
	v_pk_add_f32 v[112:113], v[112:113], v[122:123]
	v_mul_f32_e32 v110, v110, v111
	v_mul_f32_e32 v96, v96, v97
	v_mul_f32_e32 v104, v104, v105
	v_mul_f32_e32 v98, v98, v99
	v_add_f32_e32 v112, v112, v113
	v_fmamk_f32 v112, v112, 0x3a800000, v163
	v_rsq_f32_e32 v113, v112
	s_nop 0
	v_mul_f32_e32 v113, 0xbfb8aa3b, v113
	v_mul_f32_e32 v101, v113, v101
	v_mul_f32_e32 v109, v113, v109
	v_mul_f32_e32 v157, v113, v157
	v_mul_f32_e32 v103, v113, v103
	v_mul_f32_e32 v111, v113, v111
	v_mul_f32_e32 v97, v113, v97
	v_mul_f32_e32 v105, v113, v105
	v_mul_f32_e32 v99, v113, v99
	v_exp_f32_e32 v101, v101
	v_exp_f32_e32 v109, v109
	v_exp_f32_e32 v157, v157
	v_exp_f32_e32 v103, v103
	v_exp_f32_e32 v111, v111
	v_exp_f32_e32 v97, v97
	v_exp_f32_e32 v105, v105
	v_exp_f32_e32 v99, v99
	v_fma_f32 v101, v101, v112, v112
	v_fma_f32 v109, v109, v112, v112
	v_fma_f32 v157, v157, v112, v112
	v_fma_f32 v103, v103, v112, v112
	v_fma_f32 v111, v111, v112, v112
	v_fma_f32 v97, v97, v112, v112
	v_fma_f32 v105, v105, v112, v112
	v_fma_f32 v99, v99, v112, v112
	v_rcp_f32_e32 v101, v101
	v_rcp_f32_e32 v109, v109
	v_rcp_f32_e32 v157, v157
	v_rcp_f32_e32 v103, v103
	v_rcp_f32_e32 v111, v111
	v_rcp_f32_e32 v97, v97
	v_rcp_f32_e32 v105, v105
	v_rcp_f32_e32 v99, v99
	v_mul_f32_e32 v100, v100, v101
	v_mul_f32_e32 v108, v108, v109
	v_mul_f32_e32 v156, v156, v157
	v_mul_f32_e32 v102, v102, v103
	v_mul_f32_e32 v110, v110, v111
	v_mul_f32_e32 v96, v96, v97
	v_mul_f32_e32 v104, v104, v105
	v_mul_f32_e32 v98, v98, v99
	v_cvt_pk_bf16_f32 v97, v108, v102
	v_cvt_pk_bf16_f32 v99, v104, v98
	v_cvt_pk_bf16_f32 v98, v110, v96
	v_cvt_pk_bf16_f32 v96, v156, v100
	v_mad_i64_i32 v[112:113], s[30:31], v126, s54, v[120:121]
	v_lshl_add_u64 v[112:113], v[112:113], 0, s[28:29]
	v_lshl_add_u64 v[100:101], v[112:113], 0, s[8:9]
	v_or_b32_e32 v112, 32, v154
	v_lshl_add_u64 v[100:101], v[100:101], 0, v[136:137]
	v_ashrrev_i32_e32 v113, 31, v112
	global_store_dwordx4 v[100:101], v[96:99], off nt
	v_mov_b32_e32 v114, v92
	v_mov_b32_e32 v92, v94
	v_lshlrev_b64 v[96:97], 6, v[112:113]
	v_lshl_add_u64 v[108:109], s[74:75], 0, v[96:97]
	global_load_dwordx4 v[96:99], v[108:109], off
	global_load_dwordx4 v[100:103], v[108:109], off offset:16
	global_load_dwordx4 v[104:107], v[108:109], off offset:32
	s_nop 0
	global_load_dwordx4 v[108:111], v[108:109], off offset:48
	v_mov_b32_e32 v94, v80
	v_mov_b32_e32 v80, v82
	v_mov_b32_e32 v115, v88
	v_mov_b32_e32 v88, v93
	v_mov_b32_e32 v93, v90
	v_mov_b32_e32 v90, v95
	v_mov_b32_e32 v95, v84
	v_mov_b32_e32 v84, v81
	v_mov_b32_e32 v81, v86
	v_mov_b32_e32 v86, v83
	s_waitcnt vmcnt(2)
	v_pk_add_f32 v[96:97], v[96:97], v[98:99]
	v_pk_add_f32 v[100:101], v[100:101], v[102:103]
	s_waitcnt vmcnt(0)
	v_pk_add_f32 v[104:105], v[104:105], v[106:107]
	v_pk_add_f32 v[108:109], v[108:109], v[110:111]
	v_pk_add_f32 v[96:97], v[96:97], v[100:101]
	v_pk_add_f32 v[104:105], v[104:105], v[108:109]
	v_mul_f32_e32 v114, v114, v115
	v_mul_f32_e32 v88, v88, v89
	v_mul_f32_e32 v92, v92, v93
	v_mul_f32_e32 v90, v90, v91
	v_pk_add_f32 v[96:97], v[96:97], v[104:105]
	v_mul_f32_e32 v94, v94, v95
	v_mul_f32_e32 v84, v84, v85
	v_mul_f32_e32 v80, v80, v81
	v_mul_f32_e32 v86, v86, v87
	v_add_f32_e32 v96, v96, v97
	v_fmamk_f32 v96, v96, 0x3a800000, v163
	v_rsq_f32_e32 v97, v96
	s_nop 0
	v_mul_f32_e32 v97, 0xbfb8aa3b, v97
	v_mul_f32_e32 v115, v97, v115
	v_mul_f32_e32 v89, v97, v89
	v_mul_f32_e32 v93, v97, v93
	v_mul_f32_e32 v91, v97, v91
	v_mul_f32_e32 v95, v97, v95
	v_mul_f32_e32 v85, v97, v85
	v_mul_f32_e32 v81, v97, v81
	v_mul_f32_e32 v87, v97, v87
	v_exp_f32_e32 v115, v115
	v_exp_f32_e32 v89, v89
	v_exp_f32_e32 v93, v93
	v_exp_f32_e32 v91, v91
	v_exp_f32_e32 v95, v95
	v_exp_f32_e32 v85, v85
	v_exp_f32_e32 v81, v81
	v_exp_f32_e32 v87, v87
	v_fma_f32 v115, v115, v96, v96
	v_fma_f32 v89, v89, v96, v96
	v_fma_f32 v93, v93, v96, v96
	v_fma_f32 v91, v91, v96, v96
	v_fma_f32 v95, v95, v96, v96
	v_fma_f32 v85, v85, v96, v96
	v_fma_f32 v81, v81, v96, v96
	v_fma_f32 v87, v87, v96, v96
	v_rcp_f32_e32 v115, v115
	v_rcp_f32_e32 v89, v89
	v_rcp_f32_e32 v93, v93
	v_rcp_f32_e32 v91, v91
	v_rcp_f32_e32 v95, v95
	v_rcp_f32_e32 v85, v85
	v_rcp_f32_e32 v81, v81
	v_rcp_f32_e32 v87, v87
	v_mul_f32_e32 v114, v114, v115
	v_mul_f32_e32 v88, v88, v89
	v_mul_f32_e32 v92, v92, v93
	v_mul_f32_e32 v90, v90, v91
	v_mul_f32_e32 v94, v94, v95
	v_mul_f32_e32 v84, v84, v85
	v_mul_f32_e32 v80, v80, v81
	v_mul_f32_e32 v86, v86, v87
	v_cvt_pk_bf16_f32 v81, v92, v90
	v_cvt_pk_bf16_f32 v82, v94, v84
	v_cvt_pk_bf16_f32 v83, v80, v86
	v_cvt_pk_bf16_f32 v80, v114, v88
	v_mad_i64_i32 v[96:97], s[30:31], v112, s54, v[120:121]
	v_lshl_add_u64 v[84:85], v[96:97], 0, s[28:29]
	v_lshl_add_u64 v[84:85], v[84:85], 0, s[8:9]
	v_or_b32_e32 v96, 48, v154
	v_lshl_add_u64 v[84:85], v[84:85], 0, v[136:137]
	v_ashrrev_i32_e32 v97, 31, v96
	global_store_dwordx4 v[84:85], v[80:83], off nt
	v_mov_b32_e32 v98, v76
	v_mov_b32_e32 v99, v72
	v_lshlrev_b64 v[80:81], 6, v[96:97]
	v_lshl_add_u64 v[92:93], s[74:75], 0, v[80:81]
	global_load_dwordx4 v[80:83], v[92:93], off
	global_load_dwordx4 v[84:87], v[92:93], off offset:16
	global_load_dwordx4 v[88:91], v[92:93], off offset:32
	s_nop 0
	global_load_dwordx4 v[92:95], v[92:93], off offset:48
	v_mov_b32_e32 v72, v77
	v_mov_b32_e32 v76, v78
	v_mov_b32_e32 v77, v74
	v_mov_b32_e32 v74, v79
	v_mov_b32_e32 v78, v64
	v_mov_b32_e32 v79, v68
	v_mov_b32_e32 v68, v65
	s_waitcnt vmcnt(2)
	v_pk_add_f32 v[80:81], v[80:81], v[82:83]
	v_pk_add_f32 v[84:85], v[84:85], v[86:87]
	s_waitcnt vmcnt(0)
	v_pk_add_f32 v[88:89], v[88:89], v[90:91]
	v_pk_add_f32 v[92:93], v[92:93], v[94:95]
	v_pk_add_f32 v[80:81], v[80:81], v[84:85]
	v_pk_add_f32 v[88:89], v[88:89], v[92:93]
	v_mul_f32_e32 v98, v98, v99
	v_mul_f32_e32 v72, v72, v73
	v_mul_f32_e32 v76, v76, v77
	v_mul_f32_e32 v68, v68, v69
	v_pk_add_f32 v[80:81], v[80:81], v[88:89]
	v_mul_f32_e32 v66, v66, v70
	v_mul_f32_e32 v74, v74, v75
	v_mul_f32_e32 v78, v78, v79
	v_mul_f32_e32 v67, v67, v71
	v_add_f32_e32 v80, v80, v81
	v_fmamk_f32 v80, v80, 0x3a800000, v163
	v_rsq_f32_e32 v81, v80
	s_nop 0
	v_mul_f32_e32 v81, 0xbfb8aa3b, v81
	v_mul_f32_e32 v99, v81, v99
	v_mul_f32_e32 v73, v81, v73
	v_mul_f32_e32 v77, v81, v77
	v_mul_f32_e32 v69, v81, v69
	v_mul_f32_e32 v70, v81, v70
	v_mul_f32_e32 v75, v81, v75
	v_mul_f32_e32 v79, v81, v79
	v_mul_f32_e32 v71, v81, v71
	v_exp_f32_e32 v99, v99
	v_exp_f32_e32 v73, v73
	v_exp_f32_e32 v77, v77
	v_exp_f32_e32 v69, v69
	v_exp_f32_e32 v70, v70
	v_exp_f32_e32 v75, v75
	v_exp_f32_e32 v79, v79
	v_exp_f32_e32 v71, v71
	v_fma_f32 v99, v99, v80, v80
	v_fma_f32 v73, v73, v80, v80
	v_fma_f32 v77, v77, v80, v80
	v_fma_f32 v69, v69, v80, v80
	v_fma_f32 v70, v70, v80, v80
	v_fma_f32 v75, v75, v80, v80
	v_fma_f32 v79, v79, v80, v80
	v_fma_f32 v71, v71, v80, v80
	v_rcp_f32_e32 v99, v99
	v_rcp_f32_e32 v73, v73
	v_rcp_f32_e32 v77, v77
	v_rcp_f32_e32 v69, v69
	v_rcp_f32_e32 v70, v70
	v_rcp_f32_e32 v75, v75
	v_rcp_f32_e32 v79, v79
	v_rcp_f32_e32 v71, v71
	v_mul_f32_e32 v98, v98, v99
	v_mul_f32_e32 v72, v72, v73
	v_mul_f32_e32 v76, v76, v77
	v_mul_f32_e32 v68, v68, v69
	v_mul_f32_e32 v66, v66, v70
	v_mul_f32_e32 v74, v74, v75
	v_mul_f32_e32 v78, v78, v79
	v_mul_f32_e32 v67, v67, v71
	v_cvt_pk_bf16_f32 v64, v98, v72
	v_cvt_pk_bf16_f32 v65, v76, v74
	v_cvt_pk_bf16_f32 v67, v66, v67
	v_cvt_pk_bf16_f32 v66, v78, v68
	v_mad_i64_i32 v[68:69], s[30:31], v96, s54, v[120:121]
	v_lshl_add_u64 v[68:69], v[68:69], 0, s[28:29]
	v_lshl_add_u64 v[68:69], v[68:69], 0, s[8:9]
	v_add_u32_e32 v80, 0x80, v154
	v_lshl_add_u64 v[68:69], v[68:69], 0, v[136:137]
	v_ashrrev_i32_e32 v81, 31, v80
	global_store_dwordx4 v[68:69], v[64:67], off nt
	v_mov_b32_e32 v82, v60
	v_mov_b32_e32 v83, v56
	v_lshlrev_b64 v[64:65], 6, v[80:81]
	v_lshl_add_u64 v[76:77], s[74:75], 0, v[64:65]
	global_load_dwordx4 v[64:67], v[76:77], off
	global_load_dwordx4 v[68:71], v[76:77], off offset:16
	global_load_dwordx4 v[72:75], v[76:77], off offset:32
	s_nop 0
	global_load_dwordx4 v[76:79], v[76:77], off offset:48
	v_mov_b32_e32 v56, v61
	v_mov_b32_e32 v60, v62
	v_mov_b32_e32 v61, v58
	v_mov_b32_e32 v58, v63
	v_mov_b32_e32 v62, v48
	v_mov_b32_e32 v63, v52
	v_mov_b32_e32 v52, v49
	s_waitcnt vmcnt(2)
	v_pk_add_f32 v[64:65], v[64:65], v[66:67]
	v_pk_add_f32 v[68:69], v[68:69], v[70:71]
	s_waitcnt vmcnt(0)
	v_pk_add_f32 v[72:73], v[72:73], v[74:75]
	v_pk_add_f32 v[76:77], v[76:77], v[78:79]
	v_pk_add_f32 v[64:65], v[64:65], v[68:69]
	v_pk_add_f32 v[72:73], v[72:73], v[76:77]
	v_mul_f32_e32 v82, v82, v83
	v_mul_f32_e32 v56, v56, v57
	v_mul_f32_e32 v60, v60, v61
	v_mul_f32_e32 v52, v52, v53
	v_pk_add_f32 v[64:65], v[64:65], v[72:73]
	v_mul_f32_e32 v50, v50, v54
	v_mul_f32_e32 v58, v58, v59
	v_mul_f32_e32 v62, v62, v63
	v_mul_f32_e32 v51, v51, v55
	v_add_f32_e32 v64, v64, v65
	v_fmamk_f32 v64, v64, 0x3a800000, v163
	v_rsq_f32_e32 v65, v64
	s_nop 0
	v_mul_f32_e32 v65, 0xbfb8aa3b, v65
	v_mul_f32_e32 v83, v65, v83
	v_mul_f32_e32 v57, v65, v57
	v_mul_f32_e32 v61, v65, v61
	v_mul_f32_e32 v53, v65, v53
	v_mul_f32_e32 v54, v65, v54
	v_mul_f32_e32 v59, v65, v59
	v_mul_f32_e32 v63, v65, v63
	v_mul_f32_e32 v55, v65, v55
	v_exp_f32_e32 v83, v83
	v_exp_f32_e32 v57, v57
	v_exp_f32_e32 v61, v61
	v_exp_f32_e32 v53, v53
	v_exp_f32_e32 v54, v54
	v_exp_f32_e32 v59, v59
	v_exp_f32_e32 v63, v63
	v_exp_f32_e32 v55, v55
	v_fma_f32 v83, v83, v64, v64
	v_fma_f32 v57, v57, v64, v64
	v_fma_f32 v61, v61, v64, v64
	v_fma_f32 v53, v53, v64, v64
	v_fma_f32 v54, v54, v64, v64
	v_fma_f32 v59, v59, v64, v64
	v_fma_f32 v63, v63, v64, v64
	v_fma_f32 v55, v55, v64, v64
	v_rcp_f32_e32 v83, v83
	v_rcp_f32_e32 v57, v57
	v_rcp_f32_e32 v61, v61
	v_rcp_f32_e32 v53, v53
	v_rcp_f32_e32 v54, v54
	v_rcp_f32_e32 v59, v59
	v_rcp_f32_e32 v63, v63
	v_rcp_f32_e32 v55, v55
	v_mul_f32_e32 v82, v82, v83
	v_mul_f32_e32 v56, v56, v57
	v_mul_f32_e32 v60, v60, v61
	v_mul_f32_e32 v52, v52, v53
	v_mul_f32_e32 v50, v50, v54
	v_mul_f32_e32 v58, v58, v59
	v_mul_f32_e32 v62, v62, v63
	v_mul_f32_e32 v51, v51, v55
	v_cvt_pk_bf16_f32 v48, v82, v56
	v_cvt_pk_bf16_f32 v49, v60, v58
	v_cvt_pk_bf16_f32 v51, v50, v51
	v_cvt_pk_bf16_f32 v50, v62, v52
	v_mad_i64_i32 v[52:53], s[30:31], v80, s54, v[120:121]
	v_lshl_add_u64 v[52:53], v[52:53], 0, s[28:29]
	v_lshl_add_u64 v[52:53], v[52:53], 0, s[8:9]
	v_add_u32_e32 v64, 0x90, v154
	v_lshl_add_u64 v[52:53], v[52:53], 0, v[136:137]
	v_ashrrev_i32_e32 v65, 31, v64
	global_store_dwordx4 v[52:53], v[48:51], off nt
	v_mov_b32_e32 v66, v44
	v_mov_b32_e32 v67, v40
	v_lshlrev_b64 v[48:49], 6, v[64:65]
	v_lshl_add_u64 v[60:61], s[74:75], 0, v[48:49]
	global_load_dwordx4 v[48:51], v[60:61], off
	global_load_dwordx4 v[52:55], v[60:61], off offset:16
	global_load_dwordx4 v[56:59], v[60:61], off offset:32
	s_nop 0
	global_load_dwordx4 v[60:63], v[60:61], off offset:48
	v_mov_b32_e32 v40, v45
	v_mov_b32_e32 v44, v46
	v_mov_b32_e32 v45, v42
	v_mov_b32_e32 v42, v47
	v_mov_b32_e32 v46, v32
	v_mov_b32_e32 v47, v36
	v_mov_b32_e32 v36, v33
	s_waitcnt vmcnt(2)
	v_pk_add_f32 v[48:49], v[48:49], v[50:51]
	v_pk_add_f32 v[52:53], v[52:53], v[54:55]
	s_waitcnt vmcnt(0)
	v_pk_add_f32 v[56:57], v[56:57], v[58:59]
	v_pk_add_f32 v[60:61], v[60:61], v[62:63]
	v_pk_add_f32 v[48:49], v[48:49], v[52:53]
	v_pk_add_f32 v[56:57], v[56:57], v[60:61]
	v_mul_f32_e32 v66, v66, v67
	v_mul_f32_e32 v40, v40, v41
	v_mul_f32_e32 v44, v44, v45
	v_mul_f32_e32 v36, v36, v37
	v_pk_add_f32 v[48:49], v[48:49], v[56:57]
	v_mul_f32_e32 v34, v34, v38
	v_mul_f32_e32 v42, v42, v43
	v_mul_f32_e32 v46, v46, v47
	v_mul_f32_e32 v35, v35, v39
	v_add_f32_e32 v48, v48, v49
	v_fmamk_f32 v48, v48, 0x3a800000, v163
	v_rsq_f32_e32 v49, v48
	s_nop 0
	v_mul_f32_e32 v49, 0xbfb8aa3b, v49
	v_mul_f32_e32 v67, v49, v67
	v_mul_f32_e32 v41, v49, v41
	v_mul_f32_e32 v45, v49, v45
	v_mul_f32_e32 v37, v49, v37
	v_mul_f32_e32 v38, v49, v38
	v_mul_f32_e32 v43, v49, v43
	v_mul_f32_e32 v47, v49, v47
	v_mul_f32_e32 v39, v49, v39
	v_exp_f32_e32 v67, v67
	v_exp_f32_e32 v41, v41
	v_exp_f32_e32 v45, v45
	v_exp_f32_e32 v37, v37
	v_exp_f32_e32 v38, v38
	v_exp_f32_e32 v43, v43
	v_exp_f32_e32 v47, v47
	v_exp_f32_e32 v39, v39
	v_fma_f32 v67, v67, v48, v48
	v_fma_f32 v41, v41, v48, v48
	v_fma_f32 v45, v45, v48, v48
	v_fma_f32 v37, v37, v48, v48
	v_fma_f32 v38, v38, v48, v48
	v_fma_f32 v43, v43, v48, v48
	v_fma_f32 v47, v47, v48, v48
	v_fma_f32 v39, v39, v48, v48
	v_rcp_f32_e32 v67, v67
	v_rcp_f32_e32 v41, v41
	v_rcp_f32_e32 v45, v45
	v_rcp_f32_e32 v37, v37
	v_rcp_f32_e32 v38, v38
	v_rcp_f32_e32 v43, v43
	v_rcp_f32_e32 v47, v47
	v_rcp_f32_e32 v39, v39
	v_mul_f32_e32 v66, v66, v67
	v_mul_f32_e32 v40, v40, v41
	v_mul_f32_e32 v44, v44, v45
	v_mul_f32_e32 v36, v36, v37
	v_mul_f32_e32 v34, v34, v38
	v_mul_f32_e32 v42, v42, v43
	v_mul_f32_e32 v46, v46, v47
	v_mul_f32_e32 v35, v35, v39
	v_cvt_pk_bf16_f32 v32, v66, v40
	v_cvt_pk_bf16_f32 v33, v44, v42
	v_cvt_pk_bf16_f32 v35, v34, v35
	v_cvt_pk_bf16_f32 v34, v46, v36
	v_mad_i64_i32 v[36:37], s[30:31], v64, s54, v[120:121]
	v_lshl_add_u64 v[36:37], v[36:37], 0, s[28:29]
	v_lshl_add_u64 v[36:37], v[36:37], 0, s[8:9]
	v_add_u32_e32 v48, 0xa0, v154
	v_lshl_add_u64 v[36:37], v[36:37], 0, v[136:137]
	v_ashrrev_i32_e32 v49, 31, v48
	global_store_dwordx4 v[36:37], v[32:35], off nt
	v_mov_b32_e32 v50, v28
	v_mov_b32_e32 v51, v24
	v_lshlrev_b64 v[32:33], 6, v[48:49]
	v_lshl_add_u64 v[44:45], s[74:75], 0, v[32:33]
	global_load_dwordx4 v[32:35], v[44:45], off
	global_load_dwordx4 v[36:39], v[44:45], off offset:16
	global_load_dwordx4 v[40:43], v[44:45], off offset:32
	s_nop 0
	global_load_dwordx4 v[44:47], v[44:45], off offset:48
	v_mov_b32_e32 v24, v29
	v_mov_b32_e32 v28, v30
	v_mov_b32_e32 v29, v26
	v_mov_b32_e32 v26, v31
	v_mov_b32_e32 v30, v16
	v_mov_b32_e32 v31, v20
	v_mov_b32_e32 v20, v17
	s_waitcnt vmcnt(2)
	v_pk_add_f32 v[32:33], v[32:33], v[34:35]
	v_pk_add_f32 v[36:37], v[36:37], v[38:39]
	s_waitcnt vmcnt(0)
	v_pk_add_f32 v[40:41], v[40:41], v[42:43]
	v_pk_add_f32 v[44:45], v[44:45], v[46:47]
	v_pk_add_f32 v[32:33], v[32:33], v[36:37]
	v_pk_add_f32 v[40:41], v[40:41], v[44:45]
	v_mul_f32_e32 v50, v50, v51
	v_mul_f32_e32 v24, v24, v25
	v_mul_f32_e32 v28, v28, v29
	v_mul_f32_e32 v20, v20, v21
	v_pk_add_f32 v[32:33], v[32:33], v[40:41]
	v_mul_f32_e32 v18, v18, v22
	v_mul_f32_e32 v26, v26, v27
	v_mul_f32_e32 v30, v30, v31
	v_mul_f32_e32 v19, v19, v23
	v_add_f32_e32 v32, v32, v33
	v_fmamk_f32 v32, v32, 0x3a800000, v163
	v_rsq_f32_e32 v33, v32
	s_nop 0
	v_mul_f32_e32 v33, 0xbfb8aa3b, v33
	v_mul_f32_e32 v51, v33, v51
	v_mul_f32_e32 v25, v33, v25
	v_mul_f32_e32 v29, v33, v29
	v_mul_f32_e32 v21, v33, v21
	v_mul_f32_e32 v22, v33, v22
	v_mul_f32_e32 v27, v33, v27
	v_mul_f32_e32 v31, v33, v31
	v_mul_f32_e32 v23, v33, v23
	v_exp_f32_e32 v51, v51
	v_exp_f32_e32 v25, v25
	v_exp_f32_e32 v29, v29
	v_exp_f32_e32 v21, v21
	v_exp_f32_e32 v22, v22
	v_exp_f32_e32 v27, v27
	v_exp_f32_e32 v31, v31
	v_exp_f32_e32 v23, v23
	v_fma_f32 v51, v51, v32, v32
	v_fma_f32 v25, v25, v32, v32
	v_fma_f32 v29, v29, v32, v32
	v_fma_f32 v21, v21, v32, v32
	v_fma_f32 v22, v22, v32, v32
	v_fma_f32 v27, v27, v32, v32
	v_fma_f32 v31, v31, v32, v32
	v_fma_f32 v23, v23, v32, v32
	v_rcp_f32_e32 v51, v51
	v_rcp_f32_e32 v25, v25
	v_rcp_f32_e32 v29, v29
	v_rcp_f32_e32 v21, v21
	v_rcp_f32_e32 v22, v22
	v_rcp_f32_e32 v27, v27
	v_rcp_f32_e32 v31, v31
	v_rcp_f32_e32 v23, v23
	v_mul_f32_e32 v50, v50, v51
	v_mul_f32_e32 v24, v24, v25
	v_mul_f32_e32 v28, v28, v29
	v_mul_f32_e32 v20, v20, v21
	v_mul_f32_e32 v18, v18, v22
	v_mul_f32_e32 v26, v26, v27
	v_mul_f32_e32 v30, v30, v31
	v_mul_f32_e32 v19, v19, v23
	v_cvt_pk_bf16_f32 v16, v50, v24
	v_cvt_pk_bf16_f32 v17, v28, v26
	v_cvt_pk_bf16_f32 v19, v18, v19
	v_cvt_pk_bf16_f32 v18, v30, v20
	v_mad_i64_i32 v[20:21], s[30:31], v48, s54, v[120:121]
	v_lshl_add_u64 v[20:21], v[20:21], 0, s[28:29]
	v_lshl_add_u64 v[20:21], v[20:21], 0, s[8:9]
	v_add_u32_e32 v32, 0xb0, v154
	v_lshl_add_u64 v[20:21], v[20:21], 0, v[136:137]
	v_ashrrev_i32_e32 v33, 31, v32
	global_store_dwordx4 v[20:21], v[16:19], off nt
	v_mov_b32_e32 v34, v12
	v_mov_b32_e32 v35, v8
	v_lshlrev_b64 v[16:17], 6, v[32:33]
	v_lshl_add_u64 v[28:29], s[74:75], 0, v[16:17]
	global_load_dwordx4 v[16:19], v[28:29], off
	global_load_dwordx4 v[20:23], v[28:29], off offset:16
	global_load_dwordx4 v[24:27], v[28:29], off offset:32
	s_nop 0
	global_load_dwordx4 v[28:31], v[28:29], off offset:48
	v_mov_b32_e32 v8, v13
	v_mov_b32_e32 v12, v14
	v_mov_b32_e32 v13, v10
	v_mov_b32_e32 v10, v15
	v_mov_b32_e32 v14, v0
	v_mov_b32_e32 v15, v4
	v_mov_b32_e32 v4, v1
	s_waitcnt vmcnt(2)
	v_pk_add_f32 v[16:17], v[16:17], v[18:19]
	v_pk_add_f32 v[20:21], v[20:21], v[22:23]
	s_waitcnt vmcnt(0)
	v_pk_add_f32 v[24:25], v[24:25], v[26:27]
	v_pk_add_f32 v[28:29], v[28:29], v[30:31]
	v_pk_add_f32 v[16:17], v[16:17], v[20:21]
	v_pk_add_f32 v[24:25], v[24:25], v[28:29]
	v_mul_f32_e32 v34, v34, v35
	v_mul_f32_e32 v8, v8, v9
	v_mul_f32_e32 v12, v12, v13
	v_mul_f32_e32 v4, v4, v5
	v_pk_add_f32 v[16:17], v[16:17], v[24:25]
	v_mul_f32_e32 v2, v2, v6
	v_mul_f32_e32 v10, v10, v11
	v_mul_f32_e32 v14, v14, v15
	v_mul_f32_e32 v3, v3, v7
	v_add_f32_e32 v16, v16, v17
	v_fmamk_f32 v16, v16, 0x3a800000, v163
	v_rsq_f32_e32 v17, v16
	s_nop 0
	v_mul_f32_e32 v17, 0xbfb8aa3b, v17
	v_mul_f32_e32 v35, v17, v35
	v_mul_f32_e32 v9, v17, v9
	v_mul_f32_e32 v13, v17, v13
	v_mul_f32_e32 v5, v17, v5
	v_mul_f32_e32 v6, v17, v6
	v_mul_f32_e32 v11, v17, v11
	v_mul_f32_e32 v15, v17, v15
	v_mul_f32_e32 v7, v17, v7
	v_exp_f32_e32 v35, v35
	v_exp_f32_e32 v9, v9
	v_exp_f32_e32 v13, v13
	v_exp_f32_e32 v5, v5
	v_exp_f32_e32 v6, v6
	v_exp_f32_e32 v11, v11
	v_exp_f32_e32 v15, v15
	v_exp_f32_e32 v7, v7
	v_fma_f32 v35, v35, v16, v16
	v_fma_f32 v9, v9, v16, v16
	v_fma_f32 v13, v13, v16, v16
	v_fma_f32 v5, v5, v16, v16
	v_fma_f32 v6, v6, v16, v16
	v_fma_f32 v11, v11, v16, v16
	v_fma_f32 v15, v15, v16, v16
	v_fma_f32 v7, v7, v16, v16
	v_rcp_f32_e32 v35, v35
	v_rcp_f32_e32 v9, v9
	v_rcp_f32_e32 v13, v13
	v_rcp_f32_e32 v5, v5
	v_rcp_f32_e32 v6, v6
	v_rcp_f32_e32 v11, v11
	v_rcp_f32_e32 v15, v15
	v_rcp_f32_e32 v7, v7
	v_mul_f32_e32 v34, v34, v35
	v_mul_f32_e32 v8, v8, v9
	v_mul_f32_e32 v12, v12, v13
	v_mul_f32_e32 v4, v4, v5
	v_mul_f32_e32 v2, v2, v6
	v_mul_f32_e32 v10, v10, v11
	v_mul_f32_e32 v14, v14, v15
	v_mul_f32_e32 v3, v3, v7
	v_cvt_pk_bf16_f32 v0, v34, v8
	v_cvt_pk_bf16_f32 v1, v12, v10
	v_cvt_pk_bf16_f32 v3, v2, v3
	v_cvt_pk_bf16_f32 v2, v14, v4
	v_mad_i64_i32 v[4:5], s[30:31], v32, s54, v[120:121]
	v_lshl_add_u64 v[4:5], v[4:5], 0, s[28:29]
	v_lshl_add_u64 v[4:5], v[4:5], 0, s[8:9]
	v_lshl_add_u64 v[4:5], v[4:5], 0, v[136:137]
	global_store_dwordx4 v[4:5], v[0:3], off nt
	s_andn2_b64 vcc, exec, s[4:5]
	s_mov_b64 s[4:5], -1
	s_cbranch_vccnz .LBB0_1127
	s_branch .LBB0_1161
